# combo21: combo20 + EpiUp scales every accumulator by its row rstd once, in place, at the top of the epilogue (edge-row section stores scaled registers directly: 48 masked multiplies removed; halo DPP
# baseline (speedup 1.0000x reference)
; #define PG8_LAS __attribute__((address_space(3)))
;     __device__ __forceinline__ void run(const f32x4 (&acc)[2][2][4][2], const Unit& u, const Unit& nxt, bool has_next, int ui, int wr, int wc, int fr_in, int fq_in) const {
;     ...
;         float rs[2][4];
; #pragma unroll
;         for (int ai = 0; ai < 2; ++ai)
; #pragma unroll
;             for (int m = 0; m < 4; ++m) rs[ai][m] = rsd[slot * 256 + ai * 128 + wr * 64 + 4 * fr + m];
; #pragma unroll
;         for (int bj = 0; bj < 2; ++bj)
; #pragma unroll
;             for (int n = 0; n < 2; ++n) {
;                 const int colt = bj * 128 + wc * 32 + n * 16 + 4 * fq;
;                 if (fr == 15) {
;                     *(PG8_LAS f32x4*)(xr + ((0 + wr) * 2 + 0) * 256 + colt) = acc[0][bj][2][n] * rs[0][2]; *(PG8_LAS f32x4*)(xr + ((0 + wr) * 2 + 1) * 256 + colt) = acc[0][bj][3][n] * rs[0][3];
;                     *(PG8_LAS f32x4*)(xr + ((2 + wr) * 2 + 0) * 256 + colt) = acc[1][bj][2][n] * rs[1][2]; *(PG8_LAS f32x4*)(xr + ((2 + wr) * 2 + 1) * 256 + colt) = acc[1][bj][3][n] * rs[1][3];
;                     if (wr == 1) { *(f32x4*)(eg + 2 * 256 + colt) = acc[1][bj][2][n] * rs[1][2]; *(f32x4*)(eg + 3 * 256 + colt) = acc[1][bj][3][n] * rs[1][3]; }
;                 }
;                 if (wr == 0 && fr == 0) { *(f32x4*)(eg + colt) = acc[0][bj][0][n] * rs[0][0]; *(f32x4*)(eg + 256 + colt) = acc[0][bj][1][n] * rs[0][1]; }
;             }
.LBB0_697:
	s_and_b32 s37, s16, 1
	s_lshl_b32 s35, s37, 10
	s_add_i32 s4, s69, s35
	v_lshl_add_u32 v72, v169, 4, s4
	s_mul_i32 s0, s42, 22
	ds_read_b128 v[100:103], v72
	ds_read_b128 v[72:75], v72 offset:512
	s_add_i32 s0, s0, s44
	s_ashr_i32 s1, s0, 31
	s_lshl_b64 s[0:1], s[0:1], 12
	s_add_u32 s4, s55, s0
	v_lshl_add_u32 v202, v136, 2, s58
	v_cndmask_b32_e64 v136, 0, 1, s[18:19]
	s_addc_u32 s5, s56, s1
	v_cmp_eq_u32_e64 s[16:17], 15, v169
	s_waitcnt lgkmcnt(0)
	v_pk_mul_f32 v[0:1], v[0:1], v[74:75] op_sel:[0,1]
	v_pk_mul_f32 v[2:3], v[2:3], v[74:75] op_sel:[0,1]
	v_pk_mul_f32 v[4:5], v[4:5], v[74:75] op_sel:[0,1]
	v_pk_mul_f32 v[6:7], v[6:7], v[74:75] op_sel:[0,1]
	v_pk_mul_f32 v[8:9], v[8:9], v[74:75] op_sel_hi:[1,0]
	v_pk_mul_f32 v[10:11], v[10:11], v[74:75] op_sel_hi:[1,0]
	v_pk_mul_f32 v[12:13], v[12:13], v[74:75] op_sel_hi:[1,0]
	v_pk_mul_f32 v[14:15], v[14:15], v[74:75] op_sel_hi:[1,0]
	v_pk_mul_f32 v[16:17], v[16:17], v[72:73] op_sel:[0,1]
	v_pk_mul_f32 v[18:19], v[18:19], v[72:73] op_sel:[0,1]
	v_pk_mul_f32 v[20:21], v[20:21], v[72:73] op_sel:[0,1]
	v_pk_mul_f32 v[22:23], v[22:23], v[72:73] op_sel:[0,1]
	v_pk_mul_f32 v[24:25], v[24:25], v[72:73] op_sel_hi:[1,0]
	v_pk_mul_f32 v[26:27], v[26:27], v[72:73] op_sel_hi:[1,0]
	v_pk_mul_f32 v[28:29], v[28:29], v[72:73] op_sel_hi:[1,0]
	v_pk_mul_f32 v[30:31], v[30:31], v[72:73] op_sel_hi:[1,0]
	v_pk_mul_f32 v[32:33], v[32:33], v[102:103] op_sel:[0,1]
	v_pk_mul_f32 v[34:35], v[34:35], v[102:103] op_sel:[0,1]
	v_pk_mul_f32 v[36:37], v[36:37], v[102:103] op_sel:[0,1]
	v_pk_mul_f32 v[38:39], v[38:39], v[102:103] op_sel:[0,1]
	v_pk_mul_f32 v[40:41], v[40:41], v[102:103] op_sel_hi:[1,0]
	v_pk_mul_f32 v[42:43], v[42:43], v[102:103] op_sel_hi:[1,0]
	v_pk_mul_f32 v[44:45], v[44:45], v[102:103] op_sel_hi:[1,0]
	v_pk_mul_f32 v[46:47], v[46:47], v[102:103] op_sel_hi:[1,0]
	v_pk_mul_f32 v[48:49], v[48:49], v[100:101] op_sel:[0,1]
	v_pk_mul_f32 v[50:51], v[50:51], v[100:101] op_sel:[0,1]
	v_pk_mul_f32 v[52:53], v[52:53], v[100:101] op_sel:[0,1]
	v_pk_mul_f32 v[54:55], v[54:55], v[100:101] op_sel:[0,1]
	v_pk_mul_f32 v[56:57], v[56:57], v[100:101] op_sel_hi:[1,0]
	v_pk_mul_f32 v[58:59], v[58:59], v[100:101] op_sel_hi:[1,0]
	v_pk_mul_f32 v[60:61], v[60:61], v[100:101] op_sel_hi:[1,0]
	v_pk_mul_f32 v[62:63], v[62:63], v[100:101] op_sel_hi:[1,0]
	v_pk_mul_f32 v[64:65], v[64:65], v[74:75] op_sel:[0,1]
	v_pk_mul_f32 v[66:67], v[66:67], v[74:75] op_sel:[0,1]
	v_pk_mul_f32 v[68:69], v[68:69], v[74:75] op_sel:[0,1]
	v_pk_mul_f32 v[70:71], v[70:71], v[74:75] op_sel:[0,1]
	v_pk_mul_f32 v[76:77], v[76:77], v[74:75] op_sel_hi:[1,0]
	v_pk_mul_f32 v[78:79], v[78:79], v[74:75] op_sel_hi:[1,0]
	v_pk_mul_f32 v[80:81], v[80:81], v[74:75] op_sel_hi:[1,0]
	v_pk_mul_f32 v[82:83], v[82:83], v[74:75] op_sel_hi:[1,0]
	v_pk_mul_f32 v[84:85], v[84:85], v[72:73] op_sel:[0,1]
	v_pk_mul_f32 v[86:87], v[86:87], v[72:73] op_sel:[0,1]
	v_pk_mul_f32 v[88:89], v[88:89], v[72:73] op_sel:[0,1]
	v_pk_mul_f32 v[90:91], v[90:91], v[72:73] op_sel:[0,1]
	v_pk_mul_f32 v[92:93], v[92:93], v[72:73] op_sel_hi:[1,0]
	v_pk_mul_f32 v[94:95], v[94:95], v[72:73] op_sel_hi:[1,0]
	v_pk_mul_f32 v[96:97], v[96:97], v[72:73] op_sel_hi:[1,0]
	v_pk_mul_f32 v[98:99], v[98:99], v[72:73] op_sel_hi:[1,0]
	v_pk_mul_f32 v[104:105], v[104:105], v[102:103] op_sel:[0,1]
	v_pk_mul_f32 v[106:107], v[106:107], v[102:103] op_sel:[0,1]
	v_pk_mul_f32 v[108:109], v[108:109], v[102:103] op_sel:[0,1]
	v_pk_mul_f32 v[110:111], v[110:111], v[102:103] op_sel:[0,1]
	v_pk_mul_f32 v[112:113], v[112:113], v[102:103] op_sel_hi:[1,0]
	v_pk_mul_f32 v[114:115], v[114:115], v[102:103] op_sel_hi:[1,0]
	v_pk_mul_f32 v[116:117], v[116:117], v[102:103] op_sel_hi:[1,0]
	v_pk_mul_f32 v[118:119], v[118:119], v[102:103] op_sel_hi:[1,0]
	v_pk_mul_f32 v[120:121], v[120:121], v[100:101] op_sel:[0,1]
	v_pk_mul_f32 v[122:123], v[122:123], v[100:101] op_sel:[0,1]
	v_pk_mul_f32 v[124:125], v[124:125], v[100:101] op_sel:[0,1]
	v_pk_mul_f32 v[126:127], v[126:127], v[100:101] op_sel:[0,1]
	v_pk_mul_f32 v[128:129], v[128:129], v[100:101] op_sel_hi:[1,0]
	v_pk_mul_f32 v[130:131], v[130:131], v[100:101] op_sel_hi:[1,0]
	v_pk_mul_f32 v[132:133], v[132:133], v[100:101] op_sel_hi:[1,0]
	v_pk_mul_f32 v[134:135], v[134:135], v[100:101] op_sel_hi:[1,0]
	v_lshl_add_u32 v230, v202, 2, s70
	v_cmp_ne_u32_e64 s[12:13], 1, v136
	s_and_saveexec_b64 s[0:1], s[16:17]
	s_cbranch_execz .LBB0_700
	ds_write_b128 v230, v[116:119]
	ds_write_b128 v230, v[108:111] offset:1024
	s_and_b64 vcc, exec, s[12:13]
	ds_write_b128 v230, v[80:83] offset:4096
	ds_write_b128 v230, v[68:71] offset:5120
	s_cbranch_vccnz .LBB0_700
	v_ashrrev_i32_e32 v203, 31, v202
	v_lshl_add_u64 v[152:153], v[202:203], 2, s[4:5]
	global_store_dwordx4 v[152:153], v[80:83], off offset:2048
	global_store_dwordx4 v[152:153], v[68:71], off offset:3072
; #define PG8_LAS __attribute__((address_space(3)))
;     __device__ __forceinline__ void run(const f32x4 (&acc)[2][2][4][2], const Unit& u, const Unit& nxt, bool has_next, int ui, int wr, int wc, int fr_in, int fq_in) const {
;     ...
; #pragma unroll
;         for (int bj = 0; bj < 2; ++bj)
; #pragma unroll
;             for (int n = 0; n < 2; ++n) {
;                 const int colt = bj * 128 + wc * 32 + n * 16 + 4 * fq;
;                 if (fr == 15) {
;                     *(PG8_LAS f32x4*)(xr + ((0 + wr) * 2 + 0) * 256 + colt) = acc[0][bj][2][n] * rs[0][2]; *(PG8_LAS f32x4*)(xr + ((0 + wr) * 2 + 1) * 256 + colt) = acc[0][bj][3][n] * rs[0][3];
;                     *(PG8_LAS f32x4*)(xr + ((2 + wr) * 2 + 0) * 256 + colt) = acc[1][bj][2][n] * rs[1][2]; *(PG8_LAS f32x4*)(xr + ((2 + wr) * 2 + 1) * 256 + colt) = acc[1][bj][3][n] * rs[1][3];
;                     if (wr == 1) { *(f32x4*)(eg + 2 * 256 + colt) = acc[1][bj][2][n] * rs[1][2]; *(f32x4*)(eg + 3 * 256 + colt) = acc[1][bj][3][n] * rs[1][3]; }
;                 }
;                 if (wr == 0 && fr == 0) { *(f32x4*)(eg + colt) = acc[0][bj][0][n] * rs[0][0]; *(f32x4*)(eg + 256 + colt) = acc[0][bj][1][n] * rs[0][1]; }
;             }
.LBB0_700:
	s_or_b64 exec, exec, s[0:1]
	v_cmp_eq_u32_e64 s[14:15], 0, v169
	s_and_b64 s[46:47], s[26:27], s[14:15]
	v_ashrrev_i32_e32 v203, 31, v202
	s_and_saveexec_b64 s[0:1], s[46:47]
	s_cbranch_execz .LBB0_702
	v_lshl_add_u64 v[156:157], v[202:203], 2, s[4:5]
	global_store_dwordx4 v[156:157], v[132:135], off
	global_store_dwordx4 v[156:157], v[124:127], off offset:1024
.LBB0_702:
	s_or_b64 exec, exec, s[0:1]
	s_and_saveexec_b64 s[0:1], s[16:17]
	s_cbranch_execz .LBB0_705
	ds_write_b128 v230, v[44:47] offset:64
	ds_write_b128 v230, v[36:39] offset:1088
	s_and_b64 vcc, exec, s[12:13]
	ds_write_b128 v230, v[12:15] offset:4160
	ds_write_b128 v230, v[4:7] offset:5184
	s_cbranch_vccnz .LBB0_705
	v_lshl_add_u64 v[156:157], v[202:203], 2, s[4:5]
	global_store_dwordx4 v[156:157], v[12:15], off offset:2112
	global_store_dwordx4 v[156:157], v[4:7], off offset:3136
.LBB0_705:
	s_or_b64 exec, exec, s[0:1]
	s_and_saveexec_b64 s[0:1], s[46:47]
	s_cbranch_execz .LBB0_707
	v_lshl_add_u64 v[156:157], v[202:203], 2, s[4:5]
	global_store_dwordx4 v[156:157], v[60:63], off offset:64
	global_store_dwordx4 v[156:157], v[52:55], off offset:1088
.LBB0_707:
	s_or_b64 exec, exec, s[0:1]
	s_and_saveexec_b64 s[0:1], s[16:17]
	s_cbranch_execz .LBB0_710
	ds_write_b128 v230, v[112:115] offset:512
	ds_write_b128 v230, v[104:107] offset:1536
	s_and_b64 vcc, exec, s[12:13]
	ds_write_b128 v230, v[76:79] offset:4608
	ds_write_b128 v230, v[64:67] offset:5632
	s_cbranch_vccnz .LBB0_710
	v_lshl_add_u64 v[156:157], v[202:203], 2, s[4:5]
	global_store_dwordx4 v[156:157], v[76:79], off offset:2560
	global_store_dwordx4 v[156:157], v[64:67], off offset:3584
.LBB0_710:
	s_or_b64 exec, exec, s[0:1]
	s_and_saveexec_b64 s[0:1], s[46:47]
	s_cbranch_execz .LBB0_712
	v_lshl_add_u64 v[156:157], v[202:203], 2, s[4:5]
	global_store_dwordx4 v[156:157], v[128:131], off offset:512
	global_store_dwordx4 v[156:157], v[120:123], off offset:1536
.LBB0_712:
	s_or_b64 exec, exec, s[0:1]
	s_and_saveexec_b64 s[0:1], s[16:17]
	s_cbranch_execz .LBB0_715
	ds_write_b128 v230, v[40:43] offset:576
	ds_write_b128 v230, v[32:35] offset:1600
	s_and_b64 vcc, exec, s[12:13]
	ds_write_b128 v230, v[8:11] offset:4672
	ds_write_b128 v230, v[0:3] offset:5696
	s_cbranch_vccnz .LBB0_715
	v_lshl_add_u64 v[144:145], v[202:203], 2, s[4:5]
	global_store_dwordx4 v[144:145], v[8:11], off offset:2624
	global_store_dwordx4 v[144:145], v[0:3], off offset:3648
.LBB0_715:
	s_or_b64 exec, exec, s[0:1]
	s_and_saveexec_b64 s[0:1], s[46:47]
	s_cbranch_execz .LBB0_717
	v_lshl_add_u64 v[144:145], v[202:203], 2, s[4:5]
	global_store_dwordx4 v[144:145], v[56:59], off offset:576
	global_store_dwordx4 v[144:145], v[48:51], off offset:1600

;     __device__ __forceinline__ void run(const f32x4 (&acc)[2][2][4][2], const Unit& u, const Unit& nxt, bool has_next, int ui, int wr, int wc, int fr_in, int fq_in) const {
;     ...
;         for (int n = 0; n < 2; ++n) {
;             const int cl = wc * 32 + n * 16 + 4 * fq, ch = u.pn * 128 + cl;
;             const PG8_LAS float* pp = prm + slot * 1024 + cl;
;             const f32x4 wg0 = *(const PG8_LAS f32x4*)(pp), wg1 = *(const PG8_LAS f32x4*)(pp + 128), wg2 = *(const PG8_LAS f32x4*)(pp + 256), bg = *(const PG8_LAS f32x4*)(pp + 384);
;             const f32x4 wv0 = *(const PG8_LAS f32x4*)(pp + 512), wv1 = *(const PG8_LAS f32x4*)(pp + 640), wv2 = *(const PG8_LAS f32x4*)(pp + 768), bv = *(const PG8_LAS f32x4*)(pp + 896);
; #pragma unroll
;             for (int ai = 0; ai < 2; ++ai) {
;                 const int grp = 2 * ai + wr;
;                 f32x4 hg2 = {0.f, 0.f, 0.f, 0.f}, hg3 = hg2, hv2 = hg2, hv3 = hg2;
;                 if (grp > 0 && fr == 0) { const PG8_LAS float* xp = xr + ((grp - 1) * 2) * 256 + cl;
;                     hg2 = *(const PG8_LAS f32x4*)(xp); hg3 = *(const PG8_LAS f32x4*)(xp + 256); hv2 = *(const PG8_LAS f32x4*)(xp + 128); hv3 = *(const PG8_LAS f32x4*)(xp + 256 + 128); }
;                 f32x4 pg2, pg1, pv2, pv1;
;                 {
;                     const f32x4 g2 = acc[ai][0][2][n] * rs[ai][2], g3 = acc[ai][0][3][n] * rs[ai][3], v2 = acc[ai][1][2][n] * rs[ai][2], v3 = acc[ai][1][3][n] * rs[ai][3];
; #pragma unroll
;                     for (int i = 0; i < 4; ++i) {
;                         float a0 = g2[i], a1 = g3[i], a2 = v2[i], a3 = v3[i];
;                         asm volatile("" : "+v"(a0), "+v"(a1), "+v"(a2), "+v"(a3));
;                         const float t0 = DPPF(a0, 0x111), t1 = DPPF(a1, 0x111), t2 = DPPF(a2, 0x111), t3 = DPPF(a3, 0x111);
;                         pg2[i] = t0 + hg2[i]; pg1[i] = t1 + hg3[i]; pv2[i] = t2 + hv2[i]; pv1[i] = t3 + hv3[i]; }
;                 }
; #pragma unroll
;                 for (int m = 0; m < 4; ++m) {
;                     const f32x4 gc = acc[ai][0][m][n] * rs[ai][m], vc = acc[ai][1][m][n] * rs[ai][m];
;                     const f32x4 cgt = bg + wg0 * pg2 + wg1 * pg1 + wg2 * gc, cvl = bv + wv0 * pv2 + wv1 * pv1 + wv2 * vc;
;                     float a[4];
; #pragma unroll
;                     for (int i = 0; i < 4; ++i) a[i] = cgt[i] * sigmoidf_(cgt[i]) * cvl[i];
.LBB0_719:
	s_or_b64 exec, exec, s[0:1]
	s_lshl_b32 s0, s42, 8
	s_add_i32 s0, s0, s57
	v_lshl_add_u32 v231, v169, 2, s0
	v_mov_b32_dpp v234, v116 row_shr:1 row_mask:0xf bank_mask:0xf bound_ctrl:1
	s_nop 0
	v_mov_b32_dpp v240, v104 row_shr:1 row_mask:0xf bank_mask:0xf bound_ctrl:1
	v_mov_b32_dpp v236, v108 row_shr:1 row_mask:0xf bank_mask:0xf bound_ctrl:1
	v_mov_b32_dpp v238, v112 row_shr:1 row_mask:0xf bank_mask:0xf bound_ctrl:1
	v_mov_b32_dpp v235, v117 row_shr:1 row_mask:0xf bank_mask:0xf bound_ctrl:1
	v_mov_b32_dpp v237, v109 row_shr:1 row_mask:0xf bank_mask:0xf bound_ctrl:1
	v_mov_b32_dpp v239, v113 row_shr:1 row_mask:0xf bank_mask:0xf bound_ctrl:1
	s_waitcnt lgkmcnt(0)
	v_pk_add_f32 v[182:183], v[182:183], v[234:235]
	v_mov_b32_dpp v241, v105 row_shr:1 row_mask:0xf bank_mask:0xf bound_ctrl:1
	v_pk_add_f32 v[178:179], v[178:179], v[236:237]
	v_pk_fma_f32 v[182:183], v[152:153], v[182:183], v[164:165]
	v_mov_b32_dpp v242, v118 row_shr:1 row_mask:0xf bank_mask:0xf bound_ctrl:1
	v_mov_b32_dpp v248, v106 row_shr:1 row_mask:0xf bank_mask:0xf bound_ctrl:1
	v_pk_fma_f32 v[182:183], v[156:157], v[178:179], v[182:183]
	v_mov_b32_dpp v244, v110 row_shr:1 row_mask:0xf bank_mask:0xf bound_ctrl:1
	v_pk_fma_f32 v[182:183], v[132:133], v[160:161], v[182:183]
	v_mov_b32_dpp v243, v119 row_shr:1 row_mask:0xf bank_mask:0xf bound_ctrl:1
	v_exp_f32_e32 v169, v182
	v_exp_f32_e32 v235, v183
	v_mov_b32_dpp v246, v114 row_shr:1 row_mask:0xf bank_mask:0xf bound_ctrl:1
	v_add_f32_e32 v169, 1.0, v169
	v_rcp_f32_e32 v234, v169
	v_add_f32_e32 v169, 1.0, v235
	v_rcp_f32_e32 v235, v169
	v_mov_b64_e32 v[236:237], v[128:129]
	v_pk_add_f32 v[128:129], v[174:175], v[238:239]
	v_mov_b32_dpp v245, v111 row_shr:1 row_mask:0xf bank_mask:0xf bound_ctrl:1
	v_pk_mul_f32 v[174:175], v[182:183], v[234:235]
	v_pk_add_f32 v[182:183], v[184:185], v[242:243]
	v_pk_add_f32 v[180:181], v[180:181], v[244:245]
	v_pk_fma_f32 v[182:183], v[154:155], v[182:183], v[166:167]
	v_pk_fma_f32 v[182:183], v[158:159], v[180:181], v[182:183]
	v_pk_add_f32 v[170:171], v[170:171], v[240:241]
	v_pk_fma_f32 v[182:183], v[134:135], v[162:163], v[182:183]
	v_pk_fma_f32 v[128:129], v[136:137], v[128:129], v[148:149]
	v_exp_f32_e32 v169, v182
	v_exp_f32_e32 v185, v183
	v_add_f32_e32 v169, 1.0, v169
	v_pk_fma_f32 v[128:129], v[140:141], v[170:171], v[128:129]
	v_rcp_f32_e32 v184, v169
	v_add_f32_e32 v169, 1.0, v185
	v_mov_b32_dpp v247, v115 row_shr:1 row_mask:0xf bank_mask:0xf bound_ctrl:1
	v_pk_fma_f32 v[128:129], v[236:237], v[144:145], v[128:129]
	v_rcp_f32_e32 v185, v169
	v_mov_b32_dpp v249, v107 row_shr:1 row_mask:0xf bank_mask:0xf bound_ctrl:1
	v_pk_mul_f32 v[128:129], v[128:129], v[174:175]
	v_pk_add_f32 v[174:175], v[176:177], v[246:247]
	v_pk_add_f32 v[172:173], v[172:173], v[248:249]
	v_pk_fma_f32 v[174:175], v[138:139], v[174:175], v[150:151]
	s_lshl_b32 s16, s44, 7
	v_pk_fma_f32 v[174:175], v[142:143], v[172:173], v[174:175]
	v_add_u32_e32 v232, s16, v202
	v_pk_mul_f32 v[176:177], v[182:183], v[184:185]
	v_pk_fma_f32 v[174:175], v[130:131], v[146:147], v[174:175]
	v_ashrrev_i32_e32 v233, 31, v232
	v_pk_mul_f32 v[174:175], v[174:175], v[176:177]
	v_pk_fma_f32 v[178:179], v[152:153], v[178:179], v[164:165]
	v_cvt_pk_bf16_f32 v177, v174, v175
	v_lshlrev_b64 v[174:175], 1, v[232:233]
	v_mov_b32_e32 v232, v101
	v_pk_fma_f32 v[178:179], v[132:133], v[156:157], v[178:179]
	v_mov_b64_e32 v[182:183], s[20:21]
	v_pk_fma_f32 v[178:179], v[124:125], v[160:161], v[178:179]
	v_cvt_pk_bf16_f32 v176, v128, v129
	v_exp_f32_e32 v169, v178
	v_exp_f32_e32 v233, v179
	v_mad_i64_i32 v[128:129], s[0:1], v231, s74, v[182:183]
	v_lshl_add_u64 v[184:185], v[128:129], 0, v[174:175]
	v_add_f32_e32 v169, 1.0, v169
	global_store_dwordx2 v[184:185], v[176:177], off
	v_rcp_f32_e32 v176, v169
	v_add_f32_e32 v169, 1.0, v233
	v_rcp_f32_e32 v177, v169
	v_mov_b64_e32 v[184:185], v[126:127]
	v_pk_fma_f32 v[132:133], v[132:133], v[152:153], v[164:165]
	v_pk_fma_f32 v[170:171], v[136:137], v[170:171], v[148:149]
	v_pk_mul_f32 v[126:127], v[178:179], v[176:177]
	v_pk_fma_f32 v[176:177], v[154:155], v[180:181], v[166:167]
	v_pk_fma_f32 v[176:177], v[134:135], v[158:159], v[176:177]
	v_pk_fma_f32 v[132:133], v[124:125], v[156:157], v[132:133]
	v_pk_fma_f32 v[176:177], v[184:185], v[162:163], v[176:177]
	v_exp_f32_e32 v169, v176
	v_exp_f32_e32 v179, v177
	v_pk_fma_f32 v[170:171], v[236:237], v[140:141], v[170:171]
	v_add_f32_e32 v169, 1.0, v169
	v_rcp_f32_e32 v178, v169
	v_add_f32_e32 v169, 1.0, v179
	v_rcp_f32_e32 v179, v169
	v_pk_fma_f32 v[132:133], v[116:117], v[160:161], v[132:133]
	v_pk_fma_f32 v[170:171], v[120:121], v[144:145], v[170:171]
	v_pk_fma_f32 v[172:173], v[138:139], v[172:173], v[150:151]
	v_pk_mul_f32 v[126:127], v[170:171], v[126:127]
	v_pk_mul_f32 v[170:171], v[176:177], v[178:179]
	v_pk_fma_f32 v[172:173], v[130:131], v[142:143], v[172:173]
	v_exp_f32_e32 v169, v132
	v_pk_fma_f32 v[172:173], v[122:123], v[146:147], v[172:173]
	v_exp_f32_e32 v176, v133
	v_pk_mul_f32 v[170:171], v[172:173], v[170:171]
	v_cvt_pk_bf16_f32 v172, v126, v127
	v_or_b32_e32 v126, 1, v231
	v_mad_i64_i32 v[126:127], s[0:1], v126, s74, v[182:183]
	v_cvt_pk_bf16_f32 v173, v170, v171
	v_lshl_add_u64 v[170:171], v[126:127], 0, v[174:175]
	v_add_f32_e32 v169, 1.0, v169
	global_store_dwordx2 v[170:171], v[172:173], off
	v_rcp_f32_e32 v170, v169
	v_add_f32_e32 v169, 1.0, v176
	v_rcp_f32_e32 v171, v169
	v_pk_fma_f32 v[134:135], v[134:135], v[154:155], v[166:167]
	v_pk_fma_f32 v[134:135], v[184:185], v[158:159], v[134:135]
	v_pk_mul_f32 v[132:133], v[132:133], v[170:171]
	v_pk_fma_f32 v[134:135], v[118:119], v[162:163], v[134:135]
	v_exp_f32_e32 v173, v135
; __device__ __forceinline__ unsigned pk2(float lo, float hi) { f32x2_t v = {lo, hi}; bf16x2_t b = __builtin_convertvector(v, bf16x2_t); return __builtin_bit_cast(unsigned, b); }
; __device__ __forceinline__ float sigmoidf_(float v) { return fast_rcp(1.0f + fast_exp2(-v * LOG2E)); }
;     __device__ __forceinline__ void run(const f32x4 (&acc)[2][2][4][2], const Unit& u, const Unit& nxt, bool has_next, int ui, int wr, int wc, int fr_in, int fq_in) const {
;     ...
;             for (int ai = 0; ai < 2; ++ai) {
;                 const int grp = 2 * ai + wr;
;                 f32x4 hg2 = {0.f, 0.f, 0.f, 0.f}, hg3 = hg2, hv2 = hg2, hv3 = hg2;
;                 if (grp > 0 && fr == 0) { const PG8_LAS float* xp = xr + ((grp - 1) * 2) * 256 + cl;
;                     hg2 = *(const PG8_LAS f32x4*)(xp); hg3 = *(const PG8_LAS f32x4*)(xp + 256); hv2 = *(const PG8_LAS f32x4*)(xp + 128); hv3 = *(const PG8_LAS f32x4*)(xp + 256 + 128); }
;                 f32x4 pg2, pg1, pv2, pv1;
;                 {
;                     const f32x4 g2 = acc[ai][0][2][n] * rs[ai][2], g3 = acc[ai][0][3][n] * rs[ai][3], v2 = acc[ai][1][2][n] * rs[ai][2], v3 = acc[ai][1][3][n] * rs[ai][3];
; #pragma unroll
;                     for (int i = 0; i < 4; ++i) {
;                         float a0 = g2[i], a1 = g3[i], a2 = v2[i], a3 = v3[i];
;                         asm volatile("" : "+v"(a0), "+v"(a1), "+v"(a2), "+v"(a3));
;                         const float t0 = DPPF(a0, 0x111), t1 = DPPF(a1, 0x111), t2 = DPPF(a2, 0x111), t3 = DPPF(a3, 0x111);
;                         pg2[i] = t0 + hg2[i]; pg1[i] = t1 + hg3[i]; pv2[i] = t2 + hv2[i]; pv1[i] = t3 + hv3[i]; }
;                 }
; #pragma unroll
;                 for (int m = 0; m < 4; ++m) {
;                     const f32x4 gc = acc[ai][0][m][n] * rs[ai][m], vc = acc[ai][1][m][n] * rs[ai][m];
;                     const f32x4 cgt = bg + wg0 * pg2 + wg1 * pg1 + wg2 * gc, cvl = bv + wv0 * pv2 + wv1 * pv1 + wv2 * vc;
;                     float a[4];
; #pragma unroll
;                     for (int i = 0; i < 4; ++i) a[i] = cgt[i] * sigmoidf_(cgt[i]) * cvl[i];
;                     u32x2 w; w.x = pk2(a[0], a[1]); w.y = pk2(a[2], a[3]);
;                     *(u32x2*)(A + (size_t)(u.pm * BM + ai * 128 + wr * 64 + 4 * fr + m) * DFF + ch) = w;
;                     pg2 = pg1; pg1 = gc; pv2 = pv1; pv1 = vc;
;                 }
	v_pk_fma_f32 v[170:171], v[236:237], v[136:137], v[148:149]
	v_pk_fma_f32 v[124:125], v[124:125], v[152:153], v[164:165]
	v_pk_fma_f32 v[170:171], v[120:121], v[140:141], v[170:171]
	v_pk_fma_f32 v[116:117], v[116:117], v[156:157], v[124:125]
	v_pk_fma_f32 v[170:171], v[112:113], v[144:145], v[170:171]
	v_pk_mul_f32 v[132:133], v[170:171], v[132:133]
	v_mov_b32_e32 v170, v103
	v_pk_fma_f32 v[108:109], v[108:109], v[160:161], v[116:117]
	v_exp_f32_e32 v169, v134
	v_exp_f32_e32 v116, v108
	v_exp_f32_e32 v117, v109
	v_add_f32_e32 v169, 1.0, v169
	v_rcp_f32_e32 v172, v169
	v_add_f32_e32 v116, 1.0, v116
	v_add_f32_e32 v117, 1.0, v117
	v_rcp_f32_e32 v116, v116
	v_rcp_f32_e32 v117, v117
	v_add_f32_e32 v169, 1.0, v173
	v_rcp_f32_e32 v173, v169
	v_pk_mul_f32 v[108:109], v[108:109], v[116:117]
	v_pk_fma_f32 v[116:117], v[184:185], v[154:155], v[166:167]
	v_pk_fma_f32 v[116:117], v[118:119], v[158:159], v[116:117]
	v_pk_fma_f32 v[130:131], v[130:131], v[138:139], v[150:151]
	v_pk_fma_f32 v[110:111], v[110:111], v[162:163], v[116:117]
	v_pk_fma_f32 v[130:131], v[122:123], v[142:143], v[130:131]
	v_exp_f32_e32 v118, v110
	v_exp_f32_e32 v119, v111
	v_pk_fma_f32 v[116:117], v[120:121], v[136:137], v[148:149]
	v_add_f32_e32 v118, 1.0, v118
	v_rcp_f32_e32 v118, v118
	v_add_f32_e32 v119, 1.0, v119
	v_rcp_f32_e32 v119, v119
	v_pk_fma_f32 v[112:113], v[112:113], v[140:141], v[116:117]
	v_pk_fma_f32 v[104:105], v[104:105], v[144:145], v[112:113]
	v_pk_mul_f32 v[134:135], v[134:135], v[172:173]
	v_pk_mul_f32 v[104:105], v[104:105], v[108:109]
	v_pk_mul_f32 v[108:109], v[110:111], v[118:119]
	v_pk_fma_f32 v[110:111], v[122:123], v[138:139], v[150:151]
	v_pk_fma_f32 v[130:131], v[114:115], v[146:147], v[130:131]
	v_pk_fma_f32 v[110:111], v[114:115], v[142:143], v[110:111]
	v_pk_mul_f32 v[130:131], v[130:131], v[134:135]
	v_pk_fma_f32 v[106:107], v[106:107], v[146:147], v[110:111]
	v_cvt_pk_bf16_f32 v135, v130, v131
	v_pk_mul_f32 v[106:107], v[106:107], v[108:109]
	v_or_b32_e32 v130, 2, v231
	v_cvt_pk_bf16_f32 v104, v104, v105
	v_cvt_pk_bf16_f32 v105, v106, v107
	v_or_b32_e32 v106, 3, v231
	v_cvt_pk_bf16_f32 v134, v132, v133
	v_mad_i64_i32 v[132:133], s[0:1], v130, s74, v[182:183]
	v_mad_i64_i32 v[172:173], s[0:1], v106, s74, v[182:183]
	v_lshl_add_u64 v[130:131], v[132:133], 0, v[174:175]
	v_lshl_add_u64 v[106:107], v[172:173], 0, v[174:175]
	global_store_dwordx2 v[130:131], v[134:135], off
	global_store_dwordx2 v[106:107], v[104:105], off
	s_and_b64 s[14:15], s[30:31], s[14:15]
	v_mov_b32_e32 v169, 0
	v_mov_b32_e32 v170, 0
	v_mov_b32_e32 v171, 0
	v_mov_b32_e32 v104, 0
	v_mov_b32_e32 v105, 0
	v_mov_b32_e32 v106, 0
	v_mov_b32_e32 v107, 0
	v_mov_b32_e32 v108, 0
	v_mov_b32_e32 v109, 0
	v_mov_b32_e32 v110, 0
	v_mov_b32_e32 v111, 0
	v_mov_b32_e32 v112, 0
	v_mov_b32_e32 v113, 0
	v_mov_b32_e32 v114, 0
	v_mov_b32_e32 v115, 0
	s_and_saveexec_b64 s[0:1], s[14:15]
	s_cbranch_execz .LBB0_721
	ds_read_b128 v[112:115], v230 offset:2048
	ds_read_b128 v[104:107], v230 offset:2560
	ds_read_b128 v[108:111], v230 offset:3072
	ds_read_b128 v[168:171], v230 offset:3584
.LBB0_721:
	s_or_b64 exec, exec, s[0:1]
	v_mov_b32_dpp v118, v68 row_shr:1 row_mask:0xf bank_mask:0xf bound_ctrl:1
	v_mov_b32_dpp v120, v76 row_shr:1 row_mask:0xf bank_mask:0xf bound_ctrl:1
	v_mov_b32_dpp v122, v64 row_shr:1 row_mask:0xf bank_mask:0xf bound_ctrl:1
	v_mov_b32_dpp v116, v80 row_shr:1 row_mask:0xf bank_mask:0xf bound_ctrl:1
	v_mov_b32_dpp v117, v81 row_shr:1 row_mask:0xf bank_mask:0xf bound_ctrl:1
	s_waitcnt lgkmcnt(0)
	v_pk_add_f32 v[112:113], v[112:113], v[116:117]
	v_mov_b32_dpp v119, v69 row_shr:1 row_mask:0xf bank_mask:0xf bound_ctrl:1
	v_pk_add_f32 v[108:109], v[108:109], v[118:119]
	v_pk_fma_f32 v[112:113], v[152:153], v[112:113], v[164:165]
	v_pk_fma_f32 v[112:113], v[156:157], v[108:109], v[112:113]
	v_pk_fma_f32 v[112:113], v[96:97], v[160:161], v[112:113]
	v_exp_f32_e32 v116, v112
	v_exp_f32_e32 v117, v113
	v_mov_b32_dpp v121, v77 row_shr:1 row_mask:0xf bank_mask:0xf bound_ctrl:1
	v_mov_b32_dpp v123, v65 row_shr:1 row_mask:0xf bank_mask:0xf bound_ctrl:1
	v_mov_b32_dpp v130, v70 row_shr:1 row_mask:0xf bank_mask:0xf bound_ctrl:1
	v_mov_b32_dpp v134, v78 row_shr:1 row_mask:0xf bank_mask:0xf bound_ctrl:1
	v_mov_b32_dpp v178, v66 row_shr:1 row_mask:0xf bank_mask:0xf bound_ctrl:1
	v_mov_b32_dpp v124, v82 row_shr:1 row_mask:0xf bank_mask:0xf bound_ctrl:1
	v_add_f32_e32 v116, 1.0, v116
	v_add_f32_e32 v117, 1.0, v117
	v_mov_b32_dpp v125, v83 row_shr:1 row_mask:0xf bank_mask:0xf bound_ctrl:1
	v_rcp_f32_e32 v116, v116
	v_rcp_f32_e32 v117, v117
	v_mov_b32_dpp v131, v71 row_shr:1 row_mask:0xf bank_mask:0xf bound_ctrl:1
	v_pk_add_f32 v[114:115], v[114:115], v[124:125]
	v_pk_add_f32 v[110:111], v[110:111], v[130:131]
	v_pk_fma_f32 v[114:115], v[154:155], v[114:115], v[166:167]
	v_pk_fma_f32 v[114:115], v[158:159], v[110:111], v[114:115]
	v_pk_mul_f32 v[112:113], v[112:113], v[116:117]
	v_pk_fma_f32 v[114:115], v[98:99], v[162:163], v[114:115]
	v_pk_add_f32 v[104:105], v[104:105], v[120:121]
	v_exp_f32_e32 v116, v114
	v_exp_f32_e32 v117, v115
	v_pk_add_f32 v[118:119], v[168:169], v[122:123]
	v_add_f32_e32 v116, 1.0, v116
	v_add_f32_e32 v117, 1.0, v117
	v_rcp_f32_e32 v116, v116
	v_rcp_f32_e32 v117, v117
	v_pk_fma_f32 v[104:105], v[136:137], v[104:105], v[148:149]
	v_mov_b32_dpp v135, v79 row_shr:1 row_mask:0xf bank_mask:0xf bound_ctrl:1
	v_pk_fma_f32 v[104:105], v[140:141], v[118:119], v[104:105]
	v_mov_b32_dpp v179, v67 row_shr:1 row_mask:0xf bank_mask:0xf bound_ctrl:1
	v_pk_fma_f32 v[104:105], v[92:93], v[144:145], v[104:105]
	v_pk_add_f32 v[106:107], v[106:107], v[134:135]
	v_pk_mul_f32 v[114:115], v[114:115], v[116:117]
;     __device__ __forceinline__ void run(const f32x4 (&acc)[2][2][4][2], const Unit& u, const Unit& nxt, bool has_next, int ui, int wr, int wc, int fr_in, int fq_in) const {
;     ...
;         for (int n = 0; n < 2; ++n) {
;             const int cl = wc * 32 + n * 16 + 4 * fq, ch = u.pn * 128 + cl;
;             const PG8_LAS float* pp = prm + slot * 1024 + cl;
;             const f32x4 wg0 = *(const PG8_LAS f32x4*)(pp), wg1 = *(const PG8_LAS f32x4*)(pp + 128), wg2 = *(const PG8_LAS f32x4*)(pp + 256), bg = *(const PG8_LAS f32x4*)(pp + 384);
;             const f32x4 wv0 = *(const PG8_LAS f32x4*)(pp + 512), wv1 = *(const PG8_LAS f32x4*)(pp + 640), wv2 = *(const PG8_LAS f32x4*)(pp + 768), bv = *(const PG8_LAS f32x4*)(pp + 896);
; #pragma unroll
;             for (int ai = 0; ai < 2; ++ai) {
;                 const int grp = 2 * ai + wr;
;                 f32x4 hg2 = {0.f, 0.f, 0.f, 0.f}, hg3 = hg2, hv2 = hg2, hv3 = hg2;
;                 if (grp > 0 && fr == 0) { const PG8_LAS float* xp = xr + ((grp - 1) * 2) * 256 + cl;
;                     hg2 = *(const PG8_LAS f32x4*)(xp); hg3 = *(const PG8_LAS f32x4*)(xp + 256); hv2 = *(const PG8_LAS f32x4*)(xp + 128); hv3 = *(const PG8_LAS f32x4*)(xp + 256 + 128); }
;                 f32x4 pg2, pg1, pv2, pv1;
;                 {
;                     const f32x4 g2 = acc[ai][0][2][n] * rs[ai][2], g3 = acc[ai][0][3][n] * rs[ai][3], v2 = acc[ai][1][2][n] * rs[ai][2], v3 = acc[ai][1][3][n] * rs[ai][3];
; #pragma unroll
;                     for (int i = 0; i < 4; ++i) {
;                         float a0 = g2[i], a1 = g3[i], a2 = v2[i], a3 = v3[i];
;                         asm volatile("" : "+v"(a0), "+v"(a1), "+v"(a2), "+v"(a3));
;                         const float t0 = DPPF(a0, 0x111), t1 = DPPF(a1, 0x111), t2 = DPPF(a2, 0x111), t3 = DPPF(a3, 0x111);
;                         pg2[i] = t0 + hg2[i]; pg1[i] = t1 + hg3[i]; pv2[i] = t2 + hv2[i]; pv1[i] = t3 + hv3[i]; }
;                 }
; #pragma unroll
;                 for (int m = 0; m < 4; ++m) {
;                     const f32x4 gc = acc[ai][0][m][n] * rs[ai][m], vc = acc[ai][1][m][n] * rs[ai][m];
;                     const f32x4 cgt = bg + wg0 * pg2 + wg1 * pg1 + wg2 * gc, cvl = bv + wv0 * pv2 + wv1 * pv1 + wv2 * vc;
;                     float a[4];
; #pragma unroll
;                     for (int i = 0; i < 4; ++i) a[i] = cgt[i] * sigmoidf_(cgt[i]) * cvl[i];
	v_mov_b32_e32 v116, v73
	v_pk_fma_f32 v[108:109], v[152:153], v[108:109], v[164:165]
	v_pk_mul_f32 v[104:105], v[104:105], v[112:113]
	v_pk_add_f32 v[112:113], v[170:171], v[178:179]
	v_pk_fma_f32 v[106:107], v[138:139], v[106:107], v[150:151]
	v_pk_fma_f32 v[108:109], v[96:97], v[156:157], v[108:109]
	v_pk_fma_f32 v[106:107], v[142:143], v[112:113], v[106:107]
	v_pk_fma_f32 v[108:109], v[88:89], v[160:161], v[108:109]
	v_pk_fma_f32 v[106:107], v[94:95], v[146:147], v[106:107]
	v_pk_mul_f32 v[106:107], v[106:107], v[114:115]
	v_exp_f32_e32 v117, v108
	v_exp_f32_e32 v120, v109
	v_add_u32_e32 v177, 0x80, v231
	v_cvt_pk_bf16_f32 v104, v104, v105
	v_cvt_pk_bf16_f32 v105, v106, v107
	v_mov_b64_e32 v[106:107], s[20:21]
	v_mad_i64_i32 v[122:123], s[0:1], v177, s74, v[106:107]
	v_lshl_add_u64 v[114:115], v[122:123], 0, v[174:175]
	global_store_dwordx2 v[114:115], v[104:105], off
	v_add_f32_e32 v104, 1.0, v117
	v_add_f32_e32 v105, 1.0, v120
	v_rcp_f32_e32 v104, v104
	v_rcp_f32_e32 v105, v105
	v_pk_fma_f32 v[96:97], v[96:97], v[152:153], v[164:165]
	v_pk_mul_f32 v[104:105], v[108:109], v[104:105]
	v_pk_fma_f32 v[108:109], v[154:155], v[110:111], v[166:167]
	v_pk_fma_f32 v[108:109], v[98:99], v[158:159], v[108:109]
	v_pk_fma_f32 v[108:109], v[90:91], v[162:163], v[108:109]
	v_pk_fma_f32 v[96:97], v[88:89], v[156:157], v[96:97]
	v_exp_f32_e32 v114, v108
	v_exp_f32_e32 v115, v109
	v_pk_fma_f32 v[110:111], v[136:137], v[118:119], v[148:149]
	v_add_f32_e32 v114, 1.0, v114
	v_rcp_f32_e32 v114, v114
	v_add_f32_e32 v115, 1.0, v115
	v_rcp_f32_e32 v115, v115
	v_pk_fma_f32 v[110:111], v[92:93], v[140:141], v[110:111]
	v_pk_fma_f32 v[96:97], v[80:81], v[160:161], v[96:97]
	v_pk_fma_f32 v[110:111], v[84:85], v[144:145], v[110:111]
	v_pk_mul_f32 v[108:109], v[108:109], v[114:115]
	v_pk_mul_f32 v[104:105], v[110:111], v[104:105]
	v_pk_fma_f32 v[110:111], v[138:139], v[112:113], v[150:151]
	v_cvt_pk_bf16_f32 v104, v104, v105
	v_pk_fma_f32 v[110:111], v[94:95], v[142:143], v[110:111]
	v_pk_fma_f32 v[98:99], v[98:99], v[154:155], v[166:167]
	v_pk_fma_f32 v[110:111], v[86:87], v[146:147], v[110:111]
	v_pk_mul_f32 v[108:109], v[110:111], v[108:109]
	v_exp_f32_e32 v110, v96
	v_exp_f32_e32 v111, v97
	v_cvt_pk_bf16_f32 v105, v108, v109
	v_add_u32_e32 v108, 0x81, v231
	v_mad_i64_i32 v[124:125], s[0:1], v108, s74, v[106:107]
	v_lshl_add_u64 v[108:109], v[124:125], 0, v[174:175]
	global_store_dwordx2 v[108:109], v[104:105], off
	v_add_f32_e32 v104, 1.0, v110
	v_add_f32_e32 v105, 1.0, v111
	v_rcp_f32_e32 v104, v104
	v_rcp_f32_e32 v105, v105
	v_pk_fma_f32 v[98:99], v[90:91], v[158:159], v[98:99]
	v_pk_fma_f32 v[92:93], v[92:93], v[136:137], v[148:149]
	v_pk_fma_f32 v[98:99], v[82:83], v[162:163], v[98:99]
	v_pk_mul_f32 v[96:97], v[96:97], v[104:105]
	v_exp_f32_e32 v104, v98
	v_exp_f32_e32 v105, v99
	v_pk_fma_f32 v[92:93], v[84:85], v[140:141], v[92:93]
	v_add_f32_e32 v104, 1.0, v104
	v_add_f32_e32 v105, 1.0, v105
	v_rcp_f32_e32 v104, v104
	v_rcp_f32_e32 v105, v105
	v_pk_fma_f32 v[94:95], v[94:95], v[138:139], v[150:151]
	v_pk_fma_f32 v[92:93], v[76:77], v[144:145], v[92:93]
	v_pk_fma_f32 v[94:95], v[86:87], v[142:143], v[94:95]
	v_pk_mul_f32 v[92:93], v[92:93], v[96:97]
	v_pk_mul_f32 v[96:97], v[98:99], v[104:105]
	v_pk_fma_f32 v[94:95], v[78:79], v[146:147], v[94:95]
	v_pk_fma_f32 v[88:89], v[152:153], v[88:89], v[164:165]
	v_pk_mul_f32 v[94:95], v[94:95], v[96:97]
	v_mov_b32_e32 v96, v75
	v_pk_fma_f32 v[80:81], v[156:157], v[80:81], v[88:89]
	v_pk_fma_f32 v[68:69], v[160:161], v[68:69], v[80:81]
	v_exp_f32_e32 v80, v68
	v_exp_f32_e32 v81, v69
	v_cvt_pk_bf16_f32 v92, v92, v93
	v_add_f32_e32 v80, 1.0, v80
	v_add_f32_e32 v81, 1.0, v81
	v_rcp_f32_e32 v80, v80
	v_rcp_f32_e32 v81, v81
	v_cvt_pk_bf16_f32 v93, v94, v95
	v_add_u32_e32 v94, 0x82, v231
	v_mad_i64_i32 v[130:131], s[0:1], v94, s74, v[106:107]
	v_pk_mul_f32 v[68:69], v[68:69], v[80:81]
	v_pk_fma_f32 v[80:81], v[154:155], v[90:91], v[166:167]
	v_lshl_add_u64 v[94:95], v[130:131], 0, v[174:175]
	v_pk_fma_f32 v[80:81], v[158:159], v[82:83], v[80:81]
	global_store_dwordx2 v[94:95], v[92:93], off
	v_pk_fma_f32 v[70:71], v[162:163], v[70:71], v[80:81]
	v_add_u32_e32 v176, 16, v202
	v_exp_f32_e32 v82, v70
	v_exp_f32_e32 v83, v71
	v_pk_fma_f32 v[80:81], v[84:85], v[136:137], v[148:149]
	v_add_f32_e32 v82, 1.0, v82
	v_rcp_f32_e32 v82, v82
	v_add_f32_e32 v83, 1.0, v83
	v_rcp_f32_e32 v83, v83
	v_pk_fma_f32 v[76:77], v[76:77], v[140:141], v[80:81]
	v_mov_b32_e32 v104, 0
	v_pk_fma_f32 v[64:65], v[64:65], v[144:145], v[76:77]
	v_mov_b32_e32 v108, 0
	v_pk_mul_f32 v[64:65], v[64:65], v[68:69]
	v_pk_mul_f32 v[68:69], v[70:71], v[82:83]
	v_pk_fma_f32 v[70:71], v[86:87], v[138:139], v[150:151]
	v_cvt_pk_bf16_f32 v64, v64, v65
	v_pk_fma_f32 v[70:71], v[78:79], v[142:143], v[70:71]
	v_mov_b32_e32 v109, 0
	v_pk_fma_f32 v[66:67], v[66:67], v[146:147], v[70:71]
	v_mov_b32_e32 v110, 0
	v_pk_mul_f32 v[66:67], v[66:67], v[68:69]
	v_mov_b32_e32 v111, 0
	v_cvt_pk_bf16_f32 v65, v66, v67
	v_add_u32_e32 v66, 0x83, v231
	v_mad_i64_i32 v[134:135], s[0:1], v66, s74, v[106:107]
	v_lshl_add_u64 v[66:67], v[134:135], 0, v[174:175]
	global_store_dwordx2 v[66:67], v[64:65], off
	ds_read_b128 v[84:87], v203 offset:64
	ds_read_b128 v[88:91], v203 offset:576
	ds_read_b128 v[92:95], v203 offset:1088
	ds_read_b128 v[96:99], v203 offset:1600
	ds_read_b128 v[64:67], v203 offset:2112
	ds_read_b128 v[68:71], v203 offset:2624
	ds_read_b128 v[76:79], v203 offset:3136
	ds_read_b128 v[80:83], v203 offset:3648
	v_mov_b32_e32 v106, 0
	v_mov_b32_e32 v107, 0
	v_mov_b32_e32 v112, 0
	v_mov_b32_e32 v113, 0
	v_mov_b32_e32 v114, 0
	v_mov_b32_e32 v115, 0
	v_mov_b32_e32 v116, 0
	v_mov_b32_e32 v117, 0
	v_mov_b32_e32 v118, 0
	v_mov_b32_e32 v119, 0
	v_mov_b32_e32 v120, 0
	v_mov_b32_e32 v121, 0
	s_and_saveexec_b64 s[0:1], s[4:5]
	s_cbranch_execz .LBB0_723
	v_lshl_add_u32 v105, v176, 2, s71
	ds_read_b128 v[118:121], v105
	ds_read_b128 v[110:113], v105 offset:512
	ds_read_b128 v[114:117], v105 offset:1024
	ds_read_b128 v[106:109], v105 offset:1536
;     __device__ __forceinline__ void run(const f32x4 (&acc)[2][2][4][2], const Unit& u, const Unit& nxt, bool has_next, int ui, int wr, int wc, int fr_in, int fq_in) const {
;     ...
;         for (int n = 0; n < 2; ++n) {
;             const int cl = wc * 32 + n * 16 + 4 * fq, ch = u.pn * 128 + cl;
;             const PG8_LAS float* pp = prm + slot * 1024 + cl;
;             const f32x4 wg0 = *(const PG8_LAS f32x4*)(pp), wg1 = *(const PG8_LAS f32x4*)(pp + 128), wg2 = *(const PG8_LAS f32x4*)(pp + 256), bg = *(const PG8_LAS f32x4*)(pp + 384);
;             const f32x4 wv0 = *(const PG8_LAS f32x4*)(pp + 512), wv1 = *(const PG8_LAS f32x4*)(pp + 640), wv2 = *(const PG8_LAS f32x4*)(pp + 768), bv = *(const PG8_LAS f32x4*)(pp + 896);
; #pragma unroll
;             for (int ai = 0; ai < 2; ++ai) {
;                 const int grp = 2 * ai + wr;
;                 f32x4 hg2 = {0.f, 0.f, 0.f, 0.f}, hg3 = hg2, hv2 = hg2, hv3 = hg2;
;                 if (grp > 0 && fr == 0) { const PG8_LAS float* xp = xr + ((grp - 1) * 2) * 256 + cl;
;                     hg2 = *(const PG8_LAS f32x4*)(xp); hg3 = *(const PG8_LAS f32x4*)(xp + 256); hv2 = *(const PG8_LAS f32x4*)(xp + 128); hv3 = *(const PG8_LAS f32x4*)(xp + 256 + 128); }
;                 f32x4 pg2, pg1, pv2, pv1;
;                 {
;                     const f32x4 g2 = acc[ai][0][2][n] * rs[ai][2], g3 = acc[ai][0][3][n] * rs[ai][3], v2 = acc[ai][1][2][n] * rs[ai][2], v3 = acc[ai][1][3][n] * rs[ai][3];
; #pragma unroll
;                     for (int i = 0; i < 4; ++i) {
;                         float a0 = g2[i], a1 = g3[i], a2 = v2[i], a3 = v3[i];
;                         asm volatile("" : "+v"(a0), "+v"(a1), "+v"(a2), "+v"(a3));
;                         const float t0 = DPPF(a0, 0x111), t1 = DPPF(a1, 0x111), t2 = DPPF(a2, 0x111), t3 = DPPF(a3, 0x111);
;                         pg2[i] = t0 + hg2[i]; pg1[i] = t1 + hg3[i]; pv2[i] = t2 + hv2[i]; pv1[i] = t3 + hv3[i]; }
;                 }
; #pragma unroll
;                 for (int m = 0; m < 4; ++m) {
;                     const f32x4 gc = acc[ai][0][m][n] * rs[ai][m], vc = acc[ai][1][m][n] * rs[ai][m];
;                     const f32x4 cgt = bg + wg0 * pg2 + wg1 * pg1 + wg2 * gc, cvl = bv + wv0 * pv2 + wv1 * pv1 + wv2 * vc;
;                     float a[4];
; #pragma unroll
;                     for (int i = 0; i < 4; ++i) a[i] = cgt[i] * sigmoidf_(cgt[i]) * cvl[i];
.LBB0_723:
	s_or_b64 exec, exec, s[0:1]
	v_mov_b32_dpp v146, v44 row_shr:1 row_mask:0xf bank_mask:0xf bound_ctrl:1
	s_nop 0
	v_mov_b32_dpp v152, v32 row_shr:1 row_mask:0xf bank_mask:0xf bound_ctrl:1
	v_mov_b32_dpp v150, v40 row_shr:1 row_mask:0xf bank_mask:0xf bound_ctrl:1
	v_mov_b32_dpp v148, v36 row_shr:1 row_mask:0xf bank_mask:0xf bound_ctrl:1
	v_mov_b32_dpp v149, v37 row_shr:1 row_mask:0xf bank_mask:0xf bound_ctrl:1
	v_mov_b32_dpp v147, v45 row_shr:1 row_mask:0xf bank_mask:0xf bound_ctrl:1
	v_mov_b32_dpp v151, v41 row_shr:1 row_mask:0xf bank_mask:0xf bound_ctrl:1
	v_mov_b32_dpp v153, v33 row_shr:1 row_mask:0xf bank_mask:0xf bound_ctrl:1
	v_mov_b32_dpp v154, v46 row_shr:1 row_mask:0xf bank_mask:0xf bound_ctrl:1
	v_mov_b32_dpp v160, v34 row_shr:1 row_mask:0xf bank_mask:0xf bound_ctrl:1
	s_waitcnt lgkmcnt(0)
	v_pk_add_f32 v[118:119], v[118:119], v[146:147]
	v_mov_b32_e32 v140, v100
	v_mov_b32_e32 v141, v100
	v_mov_b32_dpp v158, v42 row_shr:1 row_mask:0xf bank_mask:0xf bound_ctrl:1
	v_pk_add_f32 v[114:115], v[114:115], v[148:149]
	v_pk_fma_f32 v[118:119], v[84:85], v[118:119], v[96:97]
	v_mov_b32_dpp v157, v39 row_shr:1 row_mask:0xf bank_mask:0xf bound_ctrl:1
	v_pk_fma_f32 v[118:119], v[88:89], v[114:115], v[118:119]
	v_mov_b32_dpp v159, v43 row_shr:1 row_mask:0xf bank_mask:0xf bound_ctrl:1
	v_pk_fma_f32 v[118:119], v[60:61], v[92:93], v[118:119]
	v_mov_b32_dpp v156, v38 row_shr:1 row_mask:0xf bank_mask:0xf bound_ctrl:1
	v_mov_b32_dpp v161, v35 row_shr:1 row_mask:0xf bank_mask:0xf bound_ctrl:1
	v_mov_b32_e32 v162, v100
	v_mov_b32_e32 v163, v100
	v_mov_b32_dpp v155, v47 row_shr:1 row_mask:0xf bank_mask:0xf bound_ctrl:1
	v_exp_f32_e32 v100, v118
	v_exp_f32_e32 v105, v119
	v_mov_b64_e32 v[140:141], v[56:57]
	v_add_f32_e32 v100, 1.0, v100
	v_rcp_f32_e32 v146, v100
	v_add_f32_e32 v100, 1.0, v105
	v_rcp_f32_e32 v147, v100
	v_pk_add_f32 v[56:57], v[110:111], v[150:151]
	v_pk_add_f32 v[116:117], v[116:117], v[156:157]
	v_pk_mul_f32 v[110:111], v[118:119], v[146:147]
	v_pk_add_f32 v[118:119], v[120:121], v[154:155]
	v_pk_add_f32 v[106:107], v[106:107], v[152:153]
	v_pk_fma_f32 v[118:119], v[86:87], v[118:119], v[98:99]
	v_pk_fma_f32 v[56:57], v[64:65], v[56:57], v[80:81]
	v_pk_fma_f32 v[118:119], v[90:91], v[116:117], v[118:119]
	v_pk_fma_f32 v[56:57], v[68:69], v[106:107], v[56:57]
	v_pk_fma_f32 v[118:119], v[62:63], v[94:95], v[118:119]
	v_pk_fma_f32 v[56:57], v[140:141], v[76:77], v[56:57]
	v_exp_f32_e32 v100, v118
	v_exp_f32_e32 v105, v119
	v_pk_mul_f32 v[56:57], v[56:57], v[110:111]
	v_add_f32_e32 v100, 1.0, v100
	v_rcp_f32_e32 v120, v100
	v_add_f32_e32 v100, 1.0, v105
	v_rcp_f32_e32 v121, v100
	v_pk_add_f32 v[110:111], v[112:113], v[158:159]
	v_pk_add_f32 v[108:109], v[108:109], v[160:161]
	v_pk_fma_f32 v[110:111], v[66:67], v[110:111], v[82:83]
	v_add_u32_e32 v144, s16, v176
	v_pk_fma_f32 v[110:111], v[70:71], v[108:109], v[110:111]
	v_ashrrev_i32_e32 v145, 31, v144
	v_pk_mul_f32 v[112:113], v[118:119], v[120:121]
	v_pk_fma_f32 v[110:111], v[58:59], v[78:79], v[110:111]
	v_mov_b32_e32 v142, v101
	v_pk_mul_f32 v[110:111], v[110:111], v[112:113]
	v_cvt_pk_bf16_f32 v112, v56, v57
	v_lshlrev_b64 v[56:57], 1, v[144:145]
	v_cvt_pk_bf16_f32 v113, v110, v111
	v_lshl_add_u64 v[110:111], v[128:129], 0, v[56:57]
	v_mov_b32_e32 v143, v101
	global_store_dwordx2 v[110:111], v[112:113], off
	v_pk_fma_f32 v[110:111], v[84:85], v[114:115], v[96:97]
	v_pk_fma_f32 v[110:111], v[60:61], v[88:89], v[110:111]
	v_pk_fma_f32 v[106:107], v[64:65], v[106:107], v[80:81]
	v_pk_fma_f32 v[110:111], v[52:53], v[92:93], v[110:111]
	v_exp_f32_e32 v105, v110
	v_exp_f32_e32 v113, v111
	v_mov_b32_e32 v100, v101
	v_add_f32_e32 v105, 1.0, v105
	v_rcp_f32_e32 v112, v105
	v_add_f32_e32 v105, 1.0, v113
	v_rcp_f32_e32 v113, v105
	v_pk_fma_f32 v[106:107], v[140:141], v[68:69], v[106:107]
	v_pk_mul_f32 v[100:101], v[110:111], v[112:113]
	v_pk_fma_f32 v[110:111], v[86:87], v[116:117], v[98:99]
	v_pk_fma_f32 v[108:109], v[66:67], v[108:109], v[82:83]
	v_pk_fma_f32 v[110:111], v[62:63], v[90:91], v[110:111]
	v_pk_fma_f32 v[106:107], v[48:49], v[76:77], v[106:107]
	v_pk_fma_f32 v[110:111], v[54:55], v[94:95], v[110:111]
	v_pk_fma_f32 v[108:109], v[58:59], v[70:71], v[108:109]
	v_exp_f32_e32 v105, v110
	v_exp_f32_e32 v113, v111
	v_mov_b32_e32 v138, v102
	v_add_f32_e32 v105, 1.0, v105
	v_rcp_f32_e32 v112, v105
	v_add_f32_e32 v105, 1.0, v113
	v_rcp_f32_e32 v113, v105
	v_mov_b32_e32 v139, v102
	v_pk_mul_f32 v[100:101], v[106:107], v[100:101]
	v_pk_fma_f32 v[108:109], v[50:51], v[78:79], v[108:109]
	v_pk_mul_f32 v[106:107], v[110:111], v[112:113]
	v_pk_fma_f32 v[60:61], v[60:61], v[84:85], v[96:97]
	v_pk_mul_f32 v[106:107], v[108:109], v[106:107]
	v_pk_fma_f32 v[60:61], v[52:53], v[88:89], v[60:61]
	v_cvt_pk_bf16_f32 v100, v100, v101
	v_cvt_pk_bf16_f32 v101, v106, v107
	v_lshl_add_u64 v[106:107], v[126:127], 0, v[56:57]
	v_pk_fma_f32 v[60:61], v[44:45], v[92:93], v[60:61]
	v_mov_b32_e32 v136, v103
	v_mov_b32_e32 v137, v103
	global_store_dwordx2 v[106:107], v[100:101], off
	v_pk_fma_f32 v[52:53], v[52:53], v[84:85], v[96:97]
	v_exp_f32_e32 v105, v60
	v_pk_fma_f32 v[44:45], v[44:45], v[88:89], v[52:53]
	v_exp_f32_e32 v107, v61
	v_pk_fma_f32 v[36:37], v[36:37], v[92:93], v[44:45]
	v_mov_b32_e32 v100, v102
	v_mov_b32_e32 v101, v102
	v_pk_fma_f32 v[62:63], v[62:63], v[86:87], v[98:99]
	v_pk_fma_f32 v[62:63], v[54:55], v[90:91], v[62:63]
	v_exp_f32_e32 v44, v36
	v_exp_f32_e32 v45, v37
	v_add_f32_e32 v102, 1.0, v105
	v_pk_fma_f32 v[62:63], v[46:47], v[94:95], v[62:63]
	v_rcp_f32_e32 v106, v102
	v_add_f32_e32 v102, 1.0, v107
	v_rcp_f32_e32 v107, v102
	v_exp_f32_e32 v102, v62
	v_exp_f32_e32 v105, v63
; __device__ __forceinline__ unsigned pk2(float lo, float hi) { f32x2_t v = {lo, hi}; bf16x2_t b = __builtin_convertvector(v, bf16x2_t); return __builtin_bit_cast(unsigned, b); }
; __device__ __forceinline__ float sigmoidf_(float v) { return fast_rcp(1.0f + fast_exp2(-v * LOG2E)); }
;     __device__ __forceinline__ void run(const f32x4 (&acc)[2][2][4][2], const Unit& u, const Unit& nxt, bool has_next, int ui, int wr, int wc, int fr_in, int fq_in) const {
;     ...
;             for (int ai = 0; ai < 2; ++ai) {
;                 const int grp = 2 * ai + wr;
;                 f32x4 hg2 = {0.f, 0.f, 0.f, 0.f}, hg3 = hg2, hv2 = hg2, hv3 = hg2;
;                 if (grp > 0 && fr == 0) { const PG8_LAS float* xp = xr + ((grp - 1) * 2) * 256 + cl;
;                     hg2 = *(const PG8_LAS f32x4*)(xp); hg3 = *(const PG8_LAS f32x4*)(xp + 256); hv2 = *(const PG8_LAS f32x4*)(xp + 128); hv3 = *(const PG8_LAS f32x4*)(xp + 256 + 128); }
;                 f32x4 pg2, pg1, pv2, pv1;
;                 {
;                     const f32x4 g2 = acc[ai][0][2][n] * rs[ai][2], g3 = acc[ai][0][3][n] * rs[ai][3], v2 = acc[ai][1][2][n] * rs[ai][2], v3 = acc[ai][1][3][n] * rs[ai][3];
; #pragma unroll
;                     for (int i = 0; i < 4; ++i) {
;                         float a0 = g2[i], a1 = g3[i], a2 = v2[i], a3 = v3[i];
;                         asm volatile("" : "+v"(a0), "+v"(a1), "+v"(a2), "+v"(a3));
;                         const float t0 = DPPF(a0, 0x111), t1 = DPPF(a1, 0x111), t2 = DPPF(a2, 0x111), t3 = DPPF(a3, 0x111);
;                         pg2[i] = t0 + hg2[i]; pg1[i] = t1 + hg3[i]; pv2[i] = t2 + hv2[i]; pv1[i] = t3 + hv3[i]; }
;                 }
; #pragma unroll
;                 for (int m = 0; m < 4; ++m) {
;                     const f32x4 gc = acc[ai][0][m][n] * rs[ai][m], vc = acc[ai][1][m][n] * rs[ai][m];
;                     const f32x4 cgt = bg + wg0 * pg2 + wg1 * pg1 + wg2 * gc, cvl = bv + wv0 * pv2 + wv1 * pv1 + wv2 * vc;
;                     float a[4];
; #pragma unroll
;                     for (int i = 0; i < 4; ++i) a[i] = cgt[i] * sigmoidf_(cgt[i]) * cvl[i];
;                     u32x2 w; w.x = pk2(a[0], a[1]); w.y = pk2(a[2], a[3]);
;                     *(u32x2*)(A + (size_t)(u.pm * BM + ai * 128 + wr * 64 + 4 * fr + m) * DFF + ch) = w;
;                     pg2 = pg1; pg1 = gc; pv2 = pv1; pv1 = vc;
;                 }
	v_add_f32_e32 v44, 1.0, v44
	v_add_f32_e32 v45, 1.0, v45
	v_rcp_f32_e32 v44, v44
	v_rcp_f32_e32 v45, v45
	v_add_f32_e32 v102, 1.0, v102
	v_pk_mul_f32 v[60:61], v[60:61], v[106:107]
	v_rcp_f32_e32 v106, v102
	v_add_f32_e32 v102, 1.0, v105
	v_rcp_f32_e32 v107, v102
	v_mov_b32_e32 v102, v103
	v_pk_mul_f32 v[36:37], v[36:37], v[44:45]
	v_pk_fma_f32 v[44:45], v[54:55], v[86:87], v[98:99]
	v_pk_fma_f32 v[44:45], v[46:47], v[90:91], v[44:45]
	v_pk_fma_f32 v[100:101], v[140:141], v[64:65], v[80:81]
	v_pk_fma_f32 v[38:39], v[38:39], v[94:95], v[44:45]
	v_exp_f32_e32 v46, v38
	v_exp_f32_e32 v47, v39
	v_pk_fma_f32 v[100:101], v[48:49], v[68:69], v[100:101]
	v_add_f32_e32 v46, 1.0, v46
	v_rcp_f32_e32 v46, v46
	v_add_f32_e32 v47, 1.0, v47
	v_rcp_f32_e32 v47, v47
	v_pk_fma_f32 v[44:45], v[48:49], v[64:65], v[80:81]
	v_pk_fma_f32 v[100:101], v[40:41], v[76:77], v[100:101]
	v_pk_fma_f32 v[40:41], v[40:41], v[68:69], v[44:45]
	v_pk_fma_f32 v[58:59], v[58:59], v[66:67], v[82:83]
	v_pk_fma_f32 v[32:33], v[32:33], v[76:77], v[40:41]
	v_pk_fma_f32 v[58:59], v[50:51], v[70:71], v[58:59]
	v_pk_mul_f32 v[32:33], v[32:33], v[36:37]
	v_pk_mul_f32 v[36:37], v[38:39], v[46:47]
	v_pk_fma_f32 v[38:39], v[50:51], v[66:67], v[82:83]
	v_pk_fma_f32 v[38:39], v[42:43], v[70:71], v[38:39]
	v_pk_mul_f32 v[62:63], v[62:63], v[106:107]
	v_pk_fma_f32 v[58:59], v[42:43], v[78:79], v[58:59]
	v_pk_fma_f32 v[34:35], v[34:35], v[78:79], v[38:39]
	v_pk_mul_f32 v[60:61], v[100:101], v[60:61]
	v_pk_mul_f32 v[58:59], v[58:59], v[62:63]
	v_pk_mul_f32 v[34:35], v[34:35], v[36:37]
	v_cvt_pk_bf16_f32 v60, v60, v61
	v_cvt_pk_bf16_f32 v61, v58, v59
	v_lshl_add_u64 v[58:59], v[132:133], 0, v[56:57]
	v_cvt_pk_bf16_f32 v32, v32, v33
	v_cvt_pk_bf16_f32 v33, v34, v35
	v_lshl_add_u64 v[34:35], v[172:173], 0, v[56:57]
	global_store_dwordx2 v[58:59], v[60:61], off
	global_store_dwordx2 v[34:35], v[32:33], off
	v_mov_b32_e32 v105, 0
	v_mov_b32_e32 v106, 0
	v_mov_b32_e32 v107, 0
	v_mov_b32_e32 v32, 0
	v_mov_b32_e32 v33, 0
	v_mov_b32_e32 v34, 0
	v_mov_b32_e32 v35, 0
	v_mov_b32_e32 v36, 0
	v_mov_b32_e32 v37, 0
	v_mov_b32_e32 v38, 0
	v_mov_b32_e32 v39, 0
	v_mov_b32_e32 v40, 0
	v_mov_b32_e32 v41, 0
	v_mov_b32_e32 v42, 0
	v_mov_b32_e32 v43, 0
	s_and_saveexec_b64 s[0:1], s[14:15]
	s_cbranch_execz .LBB0_725
	ds_read_b128 v[40:43], v230 offset:2112
	ds_read_b128 v[32:35], v230 offset:2624
	ds_read_b128 v[36:39], v230 offset:3136
	ds_read_b128 v[104:107], v230 offset:3648
.LBB0_725:
	s_or_b64 exec, exec, s[0:1]
	v_mov_b32_dpp v54, v4 row_shr:1 row_mask:0xf bank_mask:0xf bound_ctrl:1
	v_mov_b32_dpp v58, v8 row_shr:1 row_mask:0xf bank_mask:0xf bound_ctrl:1
	v_mov_b32_dpp v60, v0 row_shr:1 row_mask:0xf bank_mask:0xf bound_ctrl:1
	v_mov_b32_dpp v52, v12 row_shr:1 row_mask:0xf bank_mask:0xf bound_ctrl:1
	v_mov_b32_dpp v53, v13 row_shr:1 row_mask:0xf bank_mask:0xf bound_ctrl:1
	s_waitcnt lgkmcnt(0)
; __device__ __forceinline__ unsigned pk2(float lo, float hi) { f32x2_t v = {lo, hi}; bf16x2_t b = __builtin_convertvector(v, bf16x2_t); return __builtin_bit_cast(unsigned, b); }
; __device__ __forceinline__ float fast_rsq(float x) { return __builtin_amdgcn_rsqf(x); }
; __device__ __forceinline__ float sigmoidf_(float v) { return fast_rcp(1.0f + fast_exp2(-v * LOG2E)); }
;     __device__ __forceinline__ void run(const f32x4 (&acc)[2][2][4][2], const Unit& u, const Unit& nxt, bool has_next, int ui, int wr, int wc, int fr_in, int fq_in) const {
;     ...
;                 for (int m = 0; m < 4; ++m) {
;                     const f32x4 gc = acc[ai][0][m][n] * rs[ai][m], vc = acc[ai][1][m][n] * rs[ai][m];
;                     const f32x4 cgt = bg + wg0 * pg2 + wg1 * pg1 + wg2 * gc, cvl = bv + wv0 * pv2 + wv1 * pv1 + wv2 * vc;
;                     float a[4];
; #pragma unroll
;                     for (int i = 0; i < 4; ++i) a[i] = cgt[i] * sigmoidf_(cgt[i]) * cvl[i];
;                     u32x2 w; w.x = pk2(a[0], a[1]); w.y = pk2(a[2], a[3]);
;                     *(u32x2*)(A + (size_t)(u.pm * BM + ai * 128 + wr * 64 + 4 * fr + m) * DFF + ch) = w;
;                     pg2 = pg1; pg1 = gc; pv2 = pv1; pv1 = vc;
;                 }
;                 asm volatile("" ::: "memory");
;             }
;         }
;         if (has_next) {
;             prm[(slot ^ 1) * 1024 + tid] = nx0; prm[(slot ^ 1) * 1024 + tid + 512] = nx1;
;             if (tid < 256) rsd[(slot ^ 1) * 256 + tid] = fast_rsq(nrs * (1.0f / DM) + EPS);
;         }
	v_pk_add_f32 v[40:41], v[40:41], v[52:53]
	v_mov_b32_dpp v55, v5 row_shr:1 row_mask:0xf bank_mask:0xf bound_ctrl:1
	v_pk_add_f32 v[36:37], v[36:37], v[54:55]
	v_pk_fma_f32 v[40:41], v[84:85], v[40:41], v[96:97]
	v_pk_fma_f32 v[40:41], v[88:89], v[36:37], v[40:41]
	v_pk_fma_f32 v[40:41], v[28:29], v[92:93], v[40:41]
	v_mov_b32_dpp v59, v9 row_shr:1 row_mask:0xf bank_mask:0xf bound_ctrl:1
	v_exp_f32_e32 v52, v40
	v_exp_f32_e32 v53, v41
	v_mov_b32_dpp v61, v1 row_shr:1 row_mask:0xf bank_mask:0xf bound_ctrl:1
	v_mov_b32_dpp v100, v6 row_shr:1 row_mask:0xf bank_mask:0xf bound_ctrl:1
	v_mov_b32_dpp v102, v10 row_shr:1 row_mask:0xf bank_mask:0xf bound_ctrl:1
	v_mov_b32_dpp v108, v2 row_shr:1 row_mask:0xf bank_mask:0xf bound_ctrl:1
	v_mov_b32_dpp v62, v14 row_shr:1 row_mask:0xf bank_mask:0xf bound_ctrl:1
	v_add_f32_e32 v52, 1.0, v52
	v_add_f32_e32 v53, 1.0, v53
	v_mov_b32_dpp v63, v15 row_shr:1 row_mask:0xf bank_mask:0xf bound_ctrl:1
	v_rcp_f32_e32 v52, v52
	v_rcp_f32_e32 v53, v53
	v_mov_b32_dpp v101, v7 row_shr:1 row_mask:0xf bank_mask:0xf bound_ctrl:1
	v_pk_add_f32 v[42:43], v[42:43], v[62:63]
	v_mov_b32_e32 v111, v72
	v_mov_b32_dpp v103, v11 row_shr:1 row_mask:0xf bank_mask:0xf bound_ctrl:1
	v_pk_add_f32 v[38:39], v[38:39], v[100:101]
	v_pk_fma_f32 v[42:43], v[86:87], v[42:43], v[98:99]
	v_mov_b32_dpp v109, v3 row_shr:1 row_mask:0xf bank_mask:0xf bound_ctrl:1
	v_mov_b32_e32 v110, v72
	v_pk_fma_f32 v[42:43], v[90:91], v[38:39], v[42:43]
	v_pk_mul_f32 v[40:41], v[40:41], v[52:53]
	v_pk_fma_f32 v[42:43], v[30:31], v[94:95], v[42:43]
	v_pk_add_f32 v[32:33], v[32:33], v[58:59]
	v_exp_f32_e32 v52, v42
	v_exp_f32_e32 v53, v43
	v_pk_add_f32 v[48:49], v[104:105], v[60:61]
	v_pk_fma_f32 v[32:33], v[64:65], v[32:33], v[80:81]
	v_add_f32_e32 v52, 1.0, v52
	v_add_f32_e32 v53, 1.0, v53
	v_pk_fma_f32 v[32:33], v[68:69], v[48:49], v[32:33]
	v_rcp_f32_e32 v52, v52
	v_rcp_f32_e32 v53, v53
	v_pk_fma_f32 v[32:33], v[24:25], v[76:77], v[32:33]
	v_pk_add_f32 v[34:35], v[34:35], v[102:103]
	v_pk_mul_f32 v[32:33], v[32:33], v[40:41]
	v_pk_add_f32 v[40:41], v[106:107], v[108:109]
	v_pk_fma_f32 v[34:35], v[66:67], v[34:35], v[82:83]
	v_pk_fma_f32 v[34:35], v[70:71], v[40:41], v[34:35]
	v_pk_mul_f32 v[42:43], v[42:43], v[52:53]
	v_pk_fma_f32 v[34:35], v[26:27], v[78:79], v[34:35]
	v_cvt_pk_bf16_f32 v32, v32, v33
	v_pk_mul_f32 v[34:35], v[34:35], v[42:43]
	v_mov_b32_e32 v50, v73
	v_cvt_pk_bf16_f32 v33, v34, v35
	v_lshl_add_u64 v[34:35], v[122:123], 0, v[56:57]
	v_mov_b32_e32 v51, v73
	global_store_dwordx2 v[34:35], v[32:33], off
	v_pk_fma_f32 v[32:33], v[84:85], v[36:37], v[96:97]
	v_pk_fma_f32 v[32:33], v[28:29], v[88:89], v[32:33]
	v_mov_b32_e32 v72, v73
	v_pk_fma_f32 v[32:33], v[20:21], v[92:93], v[32:33]
	v_exp_f32_e32 v34, v32
	v_exp_f32_e32 v35, v33
	v_mov_b32_e32 v46, v74
	v_mov_b32_e32 v47, v74
	v_add_f32_e32 v34, 1.0, v34
	v_add_f32_e32 v35, 1.0, v35
	v_rcp_f32_e32 v34, v34
	v_rcp_f32_e32 v35, v35
	v_pk_fma_f32 v[28:29], v[28:29], v[84:85], v[96:97]
	v_mov_b32_e32 v44, v75
	v_mov_b32_e32 v45, v75
	v_pk_mul_f32 v[32:33], v[32:33], v[34:35]
	v_pk_fma_f32 v[34:35], v[86:87], v[38:39], v[98:99]
	v_pk_fma_f32 v[34:35], v[30:31], v[90:91], v[34:35]
	v_pk_fma_f32 v[28:29], v[20:21], v[88:89], v[28:29]
	v_pk_fma_f32 v[34:35], v[22:23], v[94:95], v[34:35]
	v_pk_fma_f32 v[20:21], v[20:21], v[84:85], v[96:97]
	v_exp_f32_e32 v38, v34
	v_exp_f32_e32 v39, v35
	v_pk_fma_f32 v[28:29], v[12:13], v[92:93], v[28:29]
	v_pk_fma_f32 v[12:13], v[12:13], v[88:89], v[20:21]
	v_pk_fma_f32 v[36:37], v[64:65], v[48:49], v[80:81]
	v_add_f32_e32 v38, 1.0, v38
	v_add_f32_e32 v39, 1.0, v39
	v_pk_fma_f32 v[4:5], v[4:5], v[92:93], v[12:13]
	v_rcp_f32_e32 v38, v38
	v_rcp_f32_e32 v39, v39
	v_pk_fma_f32 v[36:37], v[24:25], v[68:69], v[36:37]
	v_pk_fma_f32 v[36:37], v[16:17], v[76:77], v[36:37]
	v_exp_f32_e32 v12, v4
	v_exp_f32_e32 v13, v5
	v_pk_mul_f32 v[32:33], v[36:37], v[32:33]
	v_pk_fma_f32 v[36:37], v[66:67], v[40:41], v[82:83]
	v_pk_fma_f32 v[36:37], v[26:27], v[70:71], v[36:37]
	v_pk_mul_f32 v[34:35], v[34:35], v[38:39]
	v_pk_fma_f32 v[36:37], v[18:19], v[78:79], v[36:37]
	v_add_f32_e32 v12, 1.0, v12
	v_pk_mul_f32 v[34:35], v[36:37], v[34:35]
	v_add_f32_e32 v13, 1.0, v13
	v_cvt_pk_bf16_f32 v32, v32, v33
	v_cvt_pk_bf16_f32 v33, v34, v35
	v_lshl_add_u64 v[34:35], v[124:125], 0, v[56:57]
	v_rcp_f32_e32 v12, v12
	v_rcp_f32_e32 v13, v13
	global_store_dwordx2 v[34:35], v[32:33], off
	v_exp_f32_e32 v34, v28
	v_mov_b32_e32 v32, v74
	v_exp_f32_e32 v35, v29
	v_mov_b32_e32 v33, v74
	v_mov_b32_e32 v74, v75
	v_pk_mul_f32 v[4:5], v[4:5], v[12:13]
	v_pk_fma_f32 v[12:13], v[22:23], v[86:87], v[98:99]
	v_pk_fma_f32 v[12:13], v[14:15], v[90:91], v[12:13]
	v_pk_fma_f32 v[30:31], v[30:31], v[86:87], v[98:99]
	v_pk_fma_f32 v[6:7], v[6:7], v[94:95], v[12:13]
	v_pk_fma_f32 v[30:31], v[22:23], v[90:91], v[30:31]
	v_pk_fma_f32 v[30:31], v[14:15], v[94:95], v[30:31]
	v_exp_f32_e32 v14, v6
	v_exp_f32_e32 v15, v7
	v_exp_f32_e32 v32, v30
	v_exp_f32_e32 v33, v31
	v_add_f32_e32 v14, 1.0, v14
	v_add_f32_e32 v15, 1.0, v15
	v_add_f32_e32 v34, 1.0, v34
	v_add_f32_e32 v35, 1.0, v35
	v_pk_fma_f32 v[24:25], v[24:25], v[64:65], v[80:81]
	v_rcp_f32_e32 v14, v14
	v_rcp_f32_e32 v15, v15
	v_rcp_f32_e32 v34, v34
	v_rcp_f32_e32 v35, v35
	v_add_f32_e32 v32, 1.0, v32
	v_add_f32_e32 v33, 1.0, v33
	v_pk_fma_f32 v[24:25], v[16:17], v[68:69], v[24:25]
	v_pk_fma_f32 v[12:13], v[16:17], v[64:65], v[80:81]
	v_rcp_f32_e32 v32, v32
	v_rcp_f32_e32 v33, v33
	v_pk_fma_f32 v[24:25], v[8:9], v[76:77], v[24:25]
	v_pk_fma_f32 v[8:9], v[8:9], v[68:69], v[12:13]
	v_pk_fma_f32 v[26:27], v[26:27], v[66:67], v[82:83]
	v_pk_fma_f32 v[0:1], v[0:1], v[76:77], v[8:9]
	v_pk_mul_f32 v[28:29], v[28:29], v[34:35]
	v_pk_mul_f32 v[0:1], v[0:1], v[4:5]
	v_pk_mul_f32 v[4:5], v[6:7], v[14:15]
	v_pk_fma_f32 v[6:7], v[18:19], v[66:67], v[82:83]
	v_pk_fma_f32 v[26:27], v[18:19], v[70:71], v[26:27]
	v_pk_fma_f32 v[6:7], v[10:11], v[70:71], v[6:7]
	v_pk_mul_f32 v[24:25], v[24:25], v[28:29]
	v_pk_mul_f32 v[28:29], v[30:31], v[32:33]
	v_pk_fma_f32 v[26:27], v[10:11], v[78:79], v[26:27]
	v_pk_fma_f32 v[2:3], v[2:3], v[78:79], v[6:7]
	v_pk_mul_f32 v[26:27], v[26:27], v[28:29]
	v_pk_mul_f32 v[2:3], v[2:3], v[4:5]
	v_cvt_pk_bf16_f32 v24, v24, v25
	v_cvt_pk_bf16_f32 v25, v26, v27
	v_lshl_add_u64 v[26:27], v[130:131], 0, v[56:57]
	v_cvt_pk_bf16_f32 v0, v0, v1
	v_cvt_pk_bf16_f32 v1, v2, v3
	v_lshl_add_u64 v[2:3], v[134:135], 0, v[56:57]
	global_store_dwordx2 v[26:27], v[24:25], off
	global_store_dwordx2 v[2:3], v[0:1], off
	s_and_b64 vcc, exec, s[10:11]
	s_mov_b64 s[0:1], -1
	s_cbranch_vccnz .LBB0_681
	s_xor_b32 s4, s35, 0x400
	v_lshlrev_b32_e32 v0, 2, v226
	v_lshl_add_u32 v0, s4, 2, v0
	v_add_u32_e32 v0, 0x22040, v0
	v_cmp_gt_i32_e32 vcc, s65, v226
	s_waitcnt vmcnt(0)
	v_mul_f32_e32 v228, 0xbfb8aa3b, v228
	v_mul_f32_e32 v227, 0xbf317218, v227
	ds_write2st64_b32 v0, v228, v227 offset1:8
	s_and_saveexec_b64 s[0:1], vcc
	s_cbranch_execz .LBB0_728
	v_rsq_f32_e32 v0, v229
	v_lshl_add_u32 v1, v226, 2, s4
	v_add_u32_e32 v1, 0x24040, v1
	ds_write_b32 v1, v0

; #define PG8_LAS __attribute__((address_space(3)))
;     __device__ __forceinline__ void run(const f32x4 (&acc)[2][2][4][2], const Unit& u, const Unit& nxt, bool has_next, int ui, int wr, int wc, int fr_in, int fq_in) const {
;     ...
;         float rs[2][4];
; #pragma unroll
;         for (int ai = 0; ai < 2; ++ai)
; #pragma unroll
;             for (int m = 0; m < 4; ++m) rs[ai][m] = rsd[slot * 256 + ai * 128 + wr * 64 + 4 * fr + m];
; #pragma unroll
;         for (int bj = 0; bj < 2; ++bj)
; #pragma unroll
;             for (int n = 0; n < 2; ++n) {
;                 const int colt = bj * 128 + wc * 32 + n * 16 + 4 * fq;
;                 if (fr == 15) {
;                     *(PG8_LAS f32x4*)(xr + ((0 + wr) * 2 + 0) * 256 + colt) = acc[0][bj][2][n] * rs[0][2]; *(PG8_LAS f32x4*)(xr + ((0 + wr) * 2 + 1) * 256 + colt) = acc[0][bj][3][n] * rs[0][3];
;                     *(PG8_LAS f32x4*)(xr + ((2 + wr) * 2 + 0) * 256 + colt) = acc[1][bj][2][n] * rs[1][2]; *(PG8_LAS f32x4*)(xr + ((2 + wr) * 2 + 1) * 256 + colt) = acc[1][bj][3][n] * rs[1][3];
;                     if (wr == 1) { *(f32x4*)(eg + 2 * 256 + colt) = acc[1][bj][2][n] * rs[1][2]; *(f32x4*)(eg + 3 * 256 + colt) = acc[1][bj][3][n] * rs[1][3]; }
;                 }
;                 if (wr == 0 && fr == 0) { *(f32x4*)(eg + colt) = acc[0][bj][0][n] * rs[0][0]; *(f32x4*)(eg + 256 + colt) = acc[0][bj][1][n] * rs[0][1]; }
;             }
.LBB0_1559:
	s_and_b32 s31, s12, 1
	s_lshl_b32 s29, s31, 10
	s_add_i32 s4, s67, s29
	v_lshl_add_u32 v72, v169, 4, s4
	s_mul_i32 s0, s38, 22
	ds_read_b128 v[100:103], v72
	ds_read_b128 v[72:75], v72 offset:512
	s_add_i32 s0, s0, s40
	s_ashr_i32 s1, s0, 31
	s_lshl_b64 s[0:1], s[0:1], 12
	s_add_u32 s4, s56, s0
	v_lshl_add_u32 v202, v136, 2, s59
	v_cndmask_b32_e64 v136, 0, 1, s[14:15]
	s_addc_u32 s5, s57, s1
	v_cmp_eq_u32_e64 s[12:13], 15, v169
	s_waitcnt lgkmcnt(0)
	v_pk_mul_f32 v[0:1], v[0:1], v[74:75] op_sel:[0,1]
	v_pk_mul_f32 v[2:3], v[2:3], v[74:75] op_sel:[0,1]
	v_pk_mul_f32 v[4:5], v[4:5], v[74:75] op_sel:[0,1]
	v_pk_mul_f32 v[6:7], v[6:7], v[74:75] op_sel:[0,1]
	v_pk_mul_f32 v[8:9], v[8:9], v[74:75] op_sel_hi:[1,0]
	v_pk_mul_f32 v[10:11], v[10:11], v[74:75] op_sel_hi:[1,0]
	v_pk_mul_f32 v[12:13], v[12:13], v[74:75] op_sel_hi:[1,0]
	v_pk_mul_f32 v[14:15], v[14:15], v[74:75] op_sel_hi:[1,0]
	v_pk_mul_f32 v[16:17], v[16:17], v[72:73] op_sel:[0,1]
	v_pk_mul_f32 v[18:19], v[18:19], v[72:73] op_sel:[0,1]
	v_pk_mul_f32 v[20:21], v[20:21], v[72:73] op_sel:[0,1]
	v_pk_mul_f32 v[22:23], v[22:23], v[72:73] op_sel:[0,1]
	v_pk_mul_f32 v[24:25], v[24:25], v[72:73] op_sel_hi:[1,0]
	v_pk_mul_f32 v[26:27], v[26:27], v[72:73] op_sel_hi:[1,0]
	v_pk_mul_f32 v[28:29], v[28:29], v[72:73] op_sel_hi:[1,0]
	v_pk_mul_f32 v[30:31], v[30:31], v[72:73] op_sel_hi:[1,0]
	v_pk_mul_f32 v[32:33], v[32:33], v[102:103] op_sel:[0,1]
	v_pk_mul_f32 v[34:35], v[34:35], v[102:103] op_sel:[0,1]
	v_pk_mul_f32 v[36:37], v[36:37], v[102:103] op_sel:[0,1]
	v_pk_mul_f32 v[38:39], v[38:39], v[102:103] op_sel:[0,1]
	v_pk_mul_f32 v[40:41], v[40:41], v[102:103] op_sel_hi:[1,0]
	v_pk_mul_f32 v[42:43], v[42:43], v[102:103] op_sel_hi:[1,0]
	v_pk_mul_f32 v[44:45], v[44:45], v[102:103] op_sel_hi:[1,0]
	v_pk_mul_f32 v[46:47], v[46:47], v[102:103] op_sel_hi:[1,0]
	v_pk_mul_f32 v[48:49], v[48:49], v[100:101] op_sel:[0,1]
	v_pk_mul_f32 v[50:51], v[50:51], v[100:101] op_sel:[0,1]
	v_pk_mul_f32 v[52:53], v[52:53], v[100:101] op_sel:[0,1]
	v_pk_mul_f32 v[54:55], v[54:55], v[100:101] op_sel:[0,1]
	v_pk_mul_f32 v[56:57], v[56:57], v[100:101] op_sel_hi:[1,0]
	v_pk_mul_f32 v[58:59], v[58:59], v[100:101] op_sel_hi:[1,0]
	v_pk_mul_f32 v[60:61], v[60:61], v[100:101] op_sel_hi:[1,0]
	v_pk_mul_f32 v[62:63], v[62:63], v[100:101] op_sel_hi:[1,0]
	v_pk_mul_f32 v[64:65], v[64:65], v[74:75] op_sel:[0,1]
	v_pk_mul_f32 v[66:67], v[66:67], v[74:75] op_sel:[0,1]
	v_pk_mul_f32 v[68:69], v[68:69], v[74:75] op_sel:[0,1]
	v_pk_mul_f32 v[70:71], v[70:71], v[74:75] op_sel:[0,1]
	v_pk_mul_f32 v[76:77], v[76:77], v[74:75] op_sel_hi:[1,0]
	v_pk_mul_f32 v[78:79], v[78:79], v[74:75] op_sel_hi:[1,0]
	v_pk_mul_f32 v[80:81], v[80:81], v[74:75] op_sel_hi:[1,0]
	v_pk_mul_f32 v[82:83], v[82:83], v[74:75] op_sel_hi:[1,0]
	v_pk_mul_f32 v[84:85], v[84:85], v[72:73] op_sel:[0,1]
	v_pk_mul_f32 v[86:87], v[86:87], v[72:73] op_sel:[0,1]
	v_pk_mul_f32 v[88:89], v[88:89], v[72:73] op_sel:[0,1]
	v_pk_mul_f32 v[90:91], v[90:91], v[72:73] op_sel:[0,1]
	v_pk_mul_f32 v[92:93], v[92:93], v[72:73] op_sel_hi:[1,0]
	v_pk_mul_f32 v[94:95], v[94:95], v[72:73] op_sel_hi:[1,0]
	v_pk_mul_f32 v[96:97], v[96:97], v[72:73] op_sel_hi:[1,0]
	v_pk_mul_f32 v[98:99], v[98:99], v[72:73] op_sel_hi:[1,0]
	v_pk_mul_f32 v[104:105], v[104:105], v[102:103] op_sel:[0,1]
	v_pk_mul_f32 v[106:107], v[106:107], v[102:103] op_sel:[0,1]
	v_pk_mul_f32 v[108:109], v[108:109], v[102:103] op_sel:[0,1]
	v_pk_mul_f32 v[110:111], v[110:111], v[102:103] op_sel:[0,1]
	v_pk_mul_f32 v[112:113], v[112:113], v[102:103] op_sel_hi:[1,0]
	v_pk_mul_f32 v[114:115], v[114:115], v[102:103] op_sel_hi:[1,0]
	v_pk_mul_f32 v[116:117], v[116:117], v[102:103] op_sel_hi:[1,0]
	v_pk_mul_f32 v[118:119], v[118:119], v[102:103] op_sel_hi:[1,0]
	v_pk_mul_f32 v[120:121], v[120:121], v[100:101] op_sel:[0,1]
	v_pk_mul_f32 v[122:123], v[122:123], v[100:101] op_sel:[0,1]
	v_pk_mul_f32 v[124:125], v[124:125], v[100:101] op_sel:[0,1]
	v_pk_mul_f32 v[126:127], v[126:127], v[100:101] op_sel:[0,1]
	v_pk_mul_f32 v[128:129], v[128:129], v[100:101] op_sel_hi:[1,0]
	v_pk_mul_f32 v[130:131], v[130:131], v[100:101] op_sel_hi:[1,0]
	v_pk_mul_f32 v[132:133], v[132:133], v[100:101] op_sel_hi:[1,0]
	v_pk_mul_f32 v[134:135], v[134:135], v[100:101] op_sel_hi:[1,0]
	v_lshl_add_u32 v230, v202, 2, s68
	v_cmp_ne_u32_e64 s[8:9], 1, v136
	s_and_saveexec_b64 s[0:1], s[12:13]
	s_cbranch_execz .LBB0_1562
	ds_write_b128 v230, v[116:119]
	ds_write_b128 v230, v[108:111] offset:1024
	s_and_b64 vcc, exec, s[8:9]
	ds_write_b128 v230, v[80:83] offset:4096
	ds_write_b128 v230, v[68:71] offset:5120
	s_cbranch_vccnz .LBB0_1562
	v_ashrrev_i32_e32 v203, 31, v202
	v_lshl_add_u64 v[152:153], v[202:203], 2, s[4:5]
	global_store_dwordx4 v[152:153], v[80:83], off offset:2048
	global_store_dwordx4 v[152:153], v[68:71], off offset:3072
; #define PG8_LAS __attribute__((address_space(3)))
;     __device__ __forceinline__ void run(const f32x4 (&acc)[2][2][4][2], const Unit& u, const Unit& nxt, bool has_next, int ui, int wr, int wc, int fr_in, int fq_in) const {
;     ...
; #pragma unroll
;         for (int bj = 0; bj < 2; ++bj)
; #pragma unroll
;             for (int n = 0; n < 2; ++n) {
;                 const int colt = bj * 128 + wc * 32 + n * 16 + 4 * fq;
;                 if (fr == 15) {
;                     *(PG8_LAS f32x4*)(xr + ((0 + wr) * 2 + 0) * 256 + colt) = acc[0][bj][2][n] * rs[0][2]; *(PG8_LAS f32x4*)(xr + ((0 + wr) * 2 + 1) * 256 + colt) = acc[0][bj][3][n] * rs[0][3];
;                     *(PG8_LAS f32x4*)(xr + ((2 + wr) * 2 + 0) * 256 + colt) = acc[1][bj][2][n] * rs[1][2]; *(PG8_LAS f32x4*)(xr + ((2 + wr) * 2 + 1) * 256 + colt) = acc[1][bj][3][n] * rs[1][3];
;                     if (wr == 1) { *(f32x4*)(eg + 2 * 256 + colt) = acc[1][bj][2][n] * rs[1][2]; *(f32x4*)(eg + 3 * 256 + colt) = acc[1][bj][3][n] * rs[1][3]; }
;                 }
;                 if (wr == 0 && fr == 0) { *(f32x4*)(eg + colt) = acc[0][bj][0][n] * rs[0][0]; *(f32x4*)(eg + 256 + colt) = acc[0][bj][1][n] * rs[0][1]; }
;             }
.LBB0_1562:
	s_or_b64 exec, exec, s[0:1]
	v_cmp_eq_u32_e64 s[10:11], 0, v169
	s_and_b64 s[42:43], s[22:23], s[10:11]
	v_ashrrev_i32_e32 v203, 31, v202
	s_and_saveexec_b64 s[0:1], s[42:43]
	s_cbranch_execz .LBB0_1564
	v_lshl_add_u64 v[156:157], v[202:203], 2, s[4:5]
	global_store_dwordx4 v[156:157], v[132:135], off
	global_store_dwordx4 v[156:157], v[124:127], off offset:1024
.LBB0_1564:
	s_or_b64 exec, exec, s[0:1]
	s_and_saveexec_b64 s[0:1], s[12:13]
	s_cbranch_execz .LBB0_1567
	ds_write_b128 v230, v[44:47] offset:64
	ds_write_b128 v230, v[36:39] offset:1088
	s_and_b64 vcc, exec, s[8:9]
	ds_write_b128 v230, v[12:15] offset:4160
	ds_write_b128 v230, v[4:7] offset:5184
	s_cbranch_vccnz .LBB0_1567
	v_lshl_add_u64 v[156:157], v[202:203], 2, s[4:5]
	global_store_dwordx4 v[156:157], v[12:15], off offset:2112
	global_store_dwordx4 v[156:157], v[4:7], off offset:3136
.LBB0_1567:
	s_or_b64 exec, exec, s[0:1]
	s_and_saveexec_b64 s[0:1], s[42:43]
	s_cbranch_execz .LBB0_1569
	v_lshl_add_u64 v[156:157], v[202:203], 2, s[4:5]
	global_store_dwordx4 v[156:157], v[60:63], off offset:64
	global_store_dwordx4 v[156:157], v[52:55], off offset:1088
.LBB0_1569:
	s_or_b64 exec, exec, s[0:1]
	s_and_saveexec_b64 s[0:1], s[12:13]
	s_cbranch_execz .LBB0_1572
	ds_write_b128 v230, v[112:115] offset:512
	ds_write_b128 v230, v[104:107] offset:1536
	s_and_b64 vcc, exec, s[8:9]
	ds_write_b128 v230, v[76:79] offset:4608
	ds_write_b128 v230, v[64:67] offset:5632
	s_cbranch_vccnz .LBB0_1572
	v_lshl_add_u64 v[156:157], v[202:203], 2, s[4:5]
	global_store_dwordx4 v[156:157], v[76:79], off offset:2560
	global_store_dwordx4 v[156:157], v[64:67], off offset:3584
.LBB0_1572:
	s_or_b64 exec, exec, s[0:1]
	s_and_saveexec_b64 s[0:1], s[42:43]
	s_cbranch_execz .LBB0_1574
	v_lshl_add_u64 v[156:157], v[202:203], 2, s[4:5]
	global_store_dwordx4 v[156:157], v[128:131], off offset:512
	global_store_dwordx4 v[156:157], v[120:123], off offset:1536
.LBB0_1574:
	s_or_b64 exec, exec, s[0:1]
	s_and_saveexec_b64 s[0:1], s[12:13]
	s_cbranch_execz .LBB0_1577
	ds_write_b128 v230, v[40:43] offset:576
	ds_write_b128 v230, v[32:35] offset:1600
	s_and_b64 vcc, exec, s[8:9]
	ds_write_b128 v230, v[8:11] offset:4672
	ds_write_b128 v230, v[0:3] offset:5696
	s_cbranch_vccnz .LBB0_1577
	v_lshl_add_u64 v[144:145], v[202:203], 2, s[4:5]
	global_store_dwordx4 v[144:145], v[8:11], off offset:2624
	global_store_dwordx4 v[144:145], v[0:3], off offset:3648
.LBB0_1577:
	s_or_b64 exec, exec, s[0:1]
	s_and_saveexec_b64 s[0:1], s[42:43]
	s_cbranch_execz .LBB0_1579
	v_lshl_add_u64 v[144:145], v[202:203], 2, s[4:5]
	global_store_dwordx4 v[144:145], v[56:59], off offset:576
	global_store_dwordx4 v[144:145], v[48:51], off offset:1600

;     __device__ __forceinline__ void run(const f32x4 (&acc)[2][2][4][2], const Unit& u, const Unit& nxt, bool has_next, int ui, int wr, int wc, int fr_in, int fq_in) const {
;     ...
;         for (int n = 0; n < 2; ++n) {
;             const int cl = wc * 32 + n * 16 + 4 * fq, ch = u.pn * 128 + cl;
;             const PG8_LAS float* pp = prm + slot * 1024 + cl;
;             const f32x4 wg0 = *(const PG8_LAS f32x4*)(pp), wg1 = *(const PG8_LAS f32x4*)(pp + 128), wg2 = *(const PG8_LAS f32x4*)(pp + 256), bg = *(const PG8_LAS f32x4*)(pp + 384);
;             const f32x4 wv0 = *(const PG8_LAS f32x4*)(pp + 512), wv1 = *(const PG8_LAS f32x4*)(pp + 640), wv2 = *(const PG8_LAS f32x4*)(pp + 768), bv = *(const PG8_LAS f32x4*)(pp + 896);
; #pragma unroll
;             for (int ai = 0; ai < 2; ++ai) {
;                 const int grp = 2 * ai + wr;
;                 f32x4 hg2 = {0.f, 0.f, 0.f, 0.f}, hg3 = hg2, hv2 = hg2, hv3 = hg2;
;                 if (grp > 0 && fr == 0) { const PG8_LAS float* xp = xr + ((grp - 1) * 2) * 256 + cl;
;                     hg2 = *(const PG8_LAS f32x4*)(xp); hg3 = *(const PG8_LAS f32x4*)(xp + 256); hv2 = *(const PG8_LAS f32x4*)(xp + 128); hv3 = *(const PG8_LAS f32x4*)(xp + 256 + 128); }
;                 f32x4 pg2, pg1, pv2, pv1;
;                 {
;                     const f32x4 g2 = acc[ai][0][2][n] * rs[ai][2], g3 = acc[ai][0][3][n] * rs[ai][3], v2 = acc[ai][1][2][n] * rs[ai][2], v3 = acc[ai][1][3][n] * rs[ai][3];
; #pragma unroll
;                     for (int i = 0; i < 4; ++i) {
;                         float a0 = g2[i], a1 = g3[i], a2 = v2[i], a3 = v3[i];
;                         asm volatile("" : "+v"(a0), "+v"(a1), "+v"(a2), "+v"(a3));
;                         const float t0 = DPPF(a0, 0x111), t1 = DPPF(a1, 0x111), t2 = DPPF(a2, 0x111), t3 = DPPF(a3, 0x111);
;                         pg2[i] = t0 + hg2[i]; pg1[i] = t1 + hg3[i]; pv2[i] = t2 + hv2[i]; pv1[i] = t3 + hv3[i]; }
;                 }
; #pragma unroll
;                 for (int m = 0; m < 4; ++m) {
;                     const f32x4 gc = acc[ai][0][m][n] * rs[ai][m], vc = acc[ai][1][m][n] * rs[ai][m];
;                     const f32x4 cgt = bg + wg0 * pg2 + wg1 * pg1 + wg2 * gc, cvl = bv + wv0 * pv2 + wv1 * pv1 + wv2 * vc;
;                     float a[4];
; #pragma unroll
;                     for (int i = 0; i < 4; ++i) a[i] = cgt[i] * sigmoidf_(cgt[i]) * cvl[i];
.LBB0_1581:
	s_or_b64 exec, exec, s[0:1]
	s_lshl_b32 s0, s38, 8
	s_add_i32 s0, s0, s58
	v_lshl_add_u32 v231, v169, 2, s0
	v_mov_b32_dpp v234, v116 row_shr:1 row_mask:0xf bank_mask:0xf bound_ctrl:1
	s_nop 0
	v_mov_b32_dpp v240, v104 row_shr:1 row_mask:0xf bank_mask:0xf bound_ctrl:1
	v_mov_b32_dpp v236, v108 row_shr:1 row_mask:0xf bank_mask:0xf bound_ctrl:1
	v_mov_b32_dpp v238, v112 row_shr:1 row_mask:0xf bank_mask:0xf bound_ctrl:1
	v_mov_b32_dpp v235, v117 row_shr:1 row_mask:0xf bank_mask:0xf bound_ctrl:1
	v_mov_b32_dpp v237, v109 row_shr:1 row_mask:0xf bank_mask:0xf bound_ctrl:1
	v_mov_b32_dpp v239, v113 row_shr:1 row_mask:0xf bank_mask:0xf bound_ctrl:1
	s_waitcnt lgkmcnt(0)
	v_pk_add_f32 v[182:183], v[182:183], v[234:235]
	v_mov_b32_dpp v241, v105 row_shr:1 row_mask:0xf bank_mask:0xf bound_ctrl:1
	v_pk_add_f32 v[178:179], v[178:179], v[236:237]
	v_pk_fma_f32 v[182:183], v[152:153], v[182:183], v[164:165]
	v_mov_b32_dpp v242, v118 row_shr:1 row_mask:0xf bank_mask:0xf bound_ctrl:1
	v_mov_b32_dpp v248, v106 row_shr:1 row_mask:0xf bank_mask:0xf bound_ctrl:1
	v_pk_fma_f32 v[182:183], v[156:157], v[178:179], v[182:183]
	v_mov_b32_dpp v244, v110 row_shr:1 row_mask:0xf bank_mask:0xf bound_ctrl:1
	v_pk_fma_f32 v[182:183], v[132:133], v[160:161], v[182:183]
	v_mov_b32_dpp v243, v119 row_shr:1 row_mask:0xf bank_mask:0xf bound_ctrl:1
	v_exp_f32_e32 v169, v182
	v_exp_f32_e32 v235, v183
	v_mov_b32_dpp v246, v114 row_shr:1 row_mask:0xf bank_mask:0xf bound_ctrl:1
	v_add_f32_e32 v169, 1.0, v169
	v_rcp_f32_e32 v234, v169
	v_add_f32_e32 v169, 1.0, v235
	v_rcp_f32_e32 v235, v169
	v_mov_b64_e32 v[236:237], v[128:129]
	v_pk_add_f32 v[128:129], v[174:175], v[238:239]
	v_mov_b32_dpp v245, v111 row_shr:1 row_mask:0xf bank_mask:0xf bound_ctrl:1
	v_pk_mul_f32 v[174:175], v[182:183], v[234:235]
	v_pk_add_f32 v[182:183], v[184:185], v[242:243]
	v_pk_add_f32 v[180:181], v[180:181], v[244:245]
	v_pk_fma_f32 v[182:183], v[154:155], v[182:183], v[166:167]
	v_pk_fma_f32 v[182:183], v[158:159], v[180:181], v[182:183]
	v_pk_add_f32 v[170:171], v[170:171], v[240:241]
	v_pk_fma_f32 v[182:183], v[134:135], v[162:163], v[182:183]
	v_pk_fma_f32 v[128:129], v[136:137], v[128:129], v[148:149]
	v_exp_f32_e32 v169, v182
	v_exp_f32_e32 v185, v183
	v_add_f32_e32 v169, 1.0, v169
	v_pk_fma_f32 v[128:129], v[140:141], v[170:171], v[128:129]
	v_rcp_f32_e32 v184, v169
	v_add_f32_e32 v169, 1.0, v185
	v_mov_b32_dpp v247, v115 row_shr:1 row_mask:0xf bank_mask:0xf bound_ctrl:1
	v_pk_fma_f32 v[128:129], v[236:237], v[144:145], v[128:129]
	v_rcp_f32_e32 v185, v169
	v_mov_b32_dpp v249, v107 row_shr:1 row_mask:0xf bank_mask:0xf bound_ctrl:1
	v_pk_mul_f32 v[128:129], v[128:129], v[174:175]
	v_pk_add_f32 v[174:175], v[176:177], v[246:247]
	v_pk_add_f32 v[172:173], v[172:173], v[248:249]
	v_pk_fma_f32 v[174:175], v[138:139], v[174:175], v[150:151]
	s_lshl_b32 s12, s40, 7
	v_pk_fma_f32 v[174:175], v[142:143], v[172:173], v[174:175]
	v_add_u32_e32 v232, s12, v202
	v_pk_mul_f32 v[176:177], v[182:183], v[184:185]
	v_pk_fma_f32 v[174:175], v[130:131], v[146:147], v[174:175]
	v_ashrrev_i32_e32 v233, 31, v232
	v_pk_mul_f32 v[174:175], v[174:175], v[176:177]
	v_pk_fma_f32 v[178:179], v[152:153], v[178:179], v[164:165]
	v_cvt_pk_bf16_f32 v177, v174, v175
	v_lshlrev_b64 v[174:175], 1, v[232:233]
	v_mov_b32_e32 v232, v101
	v_pk_fma_f32 v[178:179], v[132:133], v[156:157], v[178:179]
	v_mov_b64_e32 v[182:183], s[16:17]
	v_pk_fma_f32 v[178:179], v[124:125], v[160:161], v[178:179]
	v_cvt_pk_bf16_f32 v176, v128, v129
	v_exp_f32_e32 v169, v178
	v_exp_f32_e32 v233, v179
	v_mad_i64_i32 v[128:129], s[0:1], v231, s73, v[182:183]
	v_lshl_add_u64 v[184:185], v[128:129], 0, v[174:175]
	v_add_f32_e32 v169, 1.0, v169
	global_store_dwordx2 v[184:185], v[176:177], off
	v_rcp_f32_e32 v176, v169
	v_add_f32_e32 v169, 1.0, v233
	v_rcp_f32_e32 v177, v169
	v_mov_b64_e32 v[184:185], v[126:127]
	v_pk_fma_f32 v[132:133], v[132:133], v[152:153], v[164:165]
	v_pk_fma_f32 v[170:171], v[136:137], v[170:171], v[148:149]
	v_pk_mul_f32 v[126:127], v[178:179], v[176:177]
	v_pk_fma_f32 v[176:177], v[154:155], v[180:181], v[166:167]
	v_pk_fma_f32 v[176:177], v[134:135], v[158:159], v[176:177]
	v_pk_fma_f32 v[132:133], v[124:125], v[156:157], v[132:133]
	v_pk_fma_f32 v[176:177], v[184:185], v[162:163], v[176:177]
	v_exp_f32_e32 v169, v176
	v_exp_f32_e32 v179, v177
	v_pk_fma_f32 v[170:171], v[236:237], v[140:141], v[170:171]
	v_add_f32_e32 v169, 1.0, v169
	v_rcp_f32_e32 v178, v169
	v_add_f32_e32 v169, 1.0, v179
	v_rcp_f32_e32 v179, v169
	v_pk_fma_f32 v[132:133], v[116:117], v[160:161], v[132:133]
	v_pk_fma_f32 v[170:171], v[120:121], v[144:145], v[170:171]
	v_pk_fma_f32 v[172:173], v[138:139], v[172:173], v[150:151]
	v_pk_mul_f32 v[126:127], v[170:171], v[126:127]
	v_pk_mul_f32 v[170:171], v[176:177], v[178:179]
	v_pk_fma_f32 v[172:173], v[130:131], v[142:143], v[172:173]
	v_exp_f32_e32 v169, v132
	v_pk_fma_f32 v[172:173], v[122:123], v[146:147], v[172:173]
	v_exp_f32_e32 v176, v133
	v_pk_mul_f32 v[170:171], v[172:173], v[170:171]
	v_cvt_pk_bf16_f32 v172, v126, v127
	v_or_b32_e32 v126, 1, v231
	v_mad_i64_i32 v[126:127], s[0:1], v126, s73, v[182:183]
	v_cvt_pk_bf16_f32 v173, v170, v171
	v_lshl_add_u64 v[170:171], v[126:127], 0, v[174:175]
	v_add_f32_e32 v169, 1.0, v169
	global_store_dwordx2 v[170:171], v[172:173], off
	v_rcp_f32_e32 v170, v169
	v_add_f32_e32 v169, 1.0, v176
	v_rcp_f32_e32 v171, v169
	v_pk_fma_f32 v[134:135], v[134:135], v[154:155], v[166:167]
	v_pk_fma_f32 v[134:135], v[184:185], v[158:159], v[134:135]
	v_pk_mul_f32 v[132:133], v[132:133], v[170:171]
	v_pk_fma_f32 v[134:135], v[118:119], v[162:163], v[134:135]
	v_exp_f32_e32 v173, v135
;     __device__ __forceinline__ void run(const f32x4 (&acc)[2][2][4][2], const Unit& u, const Unit& nxt, bool has_next, int ui, int wr, int wc, int fr_in, int fq_in) const {
;     ...
;         for (int n = 0; n < 2; ++n) {
;             const int cl = wc * 32 + n * 16 + 4 * fq, ch = u.pn * 128 + cl;
;             const PG8_LAS float* pp = prm + slot * 1024 + cl;
;             const f32x4 wg0 = *(const PG8_LAS f32x4*)(pp), wg1 = *(const PG8_LAS f32x4*)(pp + 128), wg2 = *(const PG8_LAS f32x4*)(pp + 256), bg = *(const PG8_LAS f32x4*)(pp + 384);
;             const f32x4 wv0 = *(const PG8_LAS f32x4*)(pp + 512), wv1 = *(const PG8_LAS f32x4*)(pp + 640), wv2 = *(const PG8_LAS f32x4*)(pp + 768), bv = *(const PG8_LAS f32x4*)(pp + 896);
; #pragma unroll
;             for (int ai = 0; ai < 2; ++ai) {
;                 const int grp = 2 * ai + wr;
;                 f32x4 hg2 = {0.f, 0.f, 0.f, 0.f}, hg3 = hg2, hv2 = hg2, hv3 = hg2;
;                 if (grp > 0 && fr == 0) { const PG8_LAS float* xp = xr + ((grp - 1) * 2) * 256 + cl;
;                     hg2 = *(const PG8_LAS f32x4*)(xp); hg3 = *(const PG8_LAS f32x4*)(xp + 256); hv2 = *(const PG8_LAS f32x4*)(xp + 128); hv3 = *(const PG8_LAS f32x4*)(xp + 256 + 128); }
;                 f32x4 pg2, pg1, pv2, pv1;
;                 {
;                     const f32x4 g2 = acc[ai][0][2][n] * rs[ai][2], g3 = acc[ai][0][3][n] * rs[ai][3], v2 = acc[ai][1][2][n] * rs[ai][2], v3 = acc[ai][1][3][n] * rs[ai][3];
; #pragma unroll
;                     for (int i = 0; i < 4; ++i) {
;                         float a0 = g2[i], a1 = g3[i], a2 = v2[i], a3 = v3[i];
;                         asm volatile("" : "+v"(a0), "+v"(a1), "+v"(a2), "+v"(a3));
;                         const float t0 = DPPF(a0, 0x111), t1 = DPPF(a1, 0x111), t2 = DPPF(a2, 0x111), t3 = DPPF(a3, 0x111);
;                         pg2[i] = t0 + hg2[i]; pg1[i] = t1 + hg3[i]; pv2[i] = t2 + hv2[i]; pv1[i] = t3 + hv3[i]; }
;                 }
; #pragma unroll
;                 for (int m = 0; m < 4; ++m) {
;                     const f32x4 gc = acc[ai][0][m][n] * rs[ai][m], vc = acc[ai][1][m][n] * rs[ai][m];
;                     const f32x4 cgt = bg + wg0 * pg2 + wg1 * pg1 + wg2 * gc, cvl = bv + wv0 * pv2 + wv1 * pv1 + wv2 * vc;
;                     float a[4];
; #pragma unroll
;                     for (int i = 0; i < 4; ++i) a[i] = cgt[i] * sigmoidf_(cgt[i]) * cvl[i];
	v_pk_fma_f32 v[170:171], v[236:237], v[136:137], v[148:149]
	v_pk_fma_f32 v[124:125], v[124:125], v[152:153], v[164:165]
	v_pk_fma_f32 v[170:171], v[120:121], v[140:141], v[170:171]
	v_pk_fma_f32 v[116:117], v[116:117], v[156:157], v[124:125]
	v_pk_fma_f32 v[170:171], v[112:113], v[144:145], v[170:171]
	v_pk_mul_f32 v[132:133], v[170:171], v[132:133]
	v_mov_b32_e32 v170, v103
	v_pk_fma_f32 v[108:109], v[108:109], v[160:161], v[116:117]
	v_exp_f32_e32 v169, v134
	v_exp_f32_e32 v116, v108
	v_exp_f32_e32 v117, v109
	v_add_f32_e32 v169, 1.0, v169
	v_rcp_f32_e32 v172, v169
	v_add_f32_e32 v116, 1.0, v116
	v_add_f32_e32 v117, 1.0, v117
	v_rcp_f32_e32 v116, v116
	v_rcp_f32_e32 v117, v117
	v_add_f32_e32 v169, 1.0, v173
	v_rcp_f32_e32 v173, v169
	v_pk_mul_f32 v[108:109], v[108:109], v[116:117]
	v_pk_fma_f32 v[116:117], v[184:185], v[154:155], v[166:167]
	v_pk_fma_f32 v[116:117], v[118:119], v[158:159], v[116:117]
	v_pk_fma_f32 v[130:131], v[130:131], v[138:139], v[150:151]
	v_pk_fma_f32 v[110:111], v[110:111], v[162:163], v[116:117]
	v_pk_fma_f32 v[130:131], v[122:123], v[142:143], v[130:131]
	v_exp_f32_e32 v118, v110
	v_exp_f32_e32 v119, v111
	v_pk_fma_f32 v[116:117], v[120:121], v[136:137], v[148:149]
	v_add_f32_e32 v118, 1.0, v118
	v_rcp_f32_e32 v118, v118
	v_add_f32_e32 v119, 1.0, v119
	v_rcp_f32_e32 v119, v119
	v_pk_fma_f32 v[112:113], v[112:113], v[140:141], v[116:117]
	v_pk_fma_f32 v[104:105], v[104:105], v[144:145], v[112:113]
	v_pk_mul_f32 v[134:135], v[134:135], v[172:173]
	v_pk_mul_f32 v[104:105], v[104:105], v[108:109]
	v_pk_mul_f32 v[108:109], v[110:111], v[118:119]
	v_pk_fma_f32 v[110:111], v[122:123], v[138:139], v[150:151]
	v_pk_fma_f32 v[130:131], v[114:115], v[146:147], v[130:131]
	v_pk_fma_f32 v[110:111], v[114:115], v[142:143], v[110:111]
	v_pk_mul_f32 v[130:131], v[130:131], v[134:135]
	v_pk_fma_f32 v[106:107], v[106:107], v[146:147], v[110:111]
	v_cvt_pk_bf16_f32 v135, v130, v131
	v_pk_mul_f32 v[106:107], v[106:107], v[108:109]
	v_or_b32_e32 v130, 2, v231
	v_cvt_pk_bf16_f32 v104, v104, v105
	v_cvt_pk_bf16_f32 v105, v106, v107
	v_or_b32_e32 v106, 3, v231
	v_cvt_pk_bf16_f32 v134, v132, v133
	v_mad_i64_i32 v[132:133], s[0:1], v130, s73, v[182:183]
	v_mad_i64_i32 v[172:173], s[0:1], v106, s73, v[182:183]
	v_lshl_add_u64 v[130:131], v[132:133], 0, v[174:175]
	v_lshl_add_u64 v[106:107], v[172:173], 0, v[174:175]
	global_store_dwordx2 v[130:131], v[134:135], off
	global_store_dwordx2 v[106:107], v[104:105], off
	s_and_b64 s[10:11], s[26:27], s[10:11]
	v_mov_b32_e32 v169, 0
	v_mov_b32_e32 v170, 0
	v_mov_b32_e32 v171, 0
	v_mov_b32_e32 v104, 0
	v_mov_b32_e32 v105, 0
	v_mov_b32_e32 v106, 0
	v_mov_b32_e32 v107, 0
	v_mov_b32_e32 v108, 0
	v_mov_b32_e32 v109, 0
	v_mov_b32_e32 v110, 0
	v_mov_b32_e32 v111, 0
	v_mov_b32_e32 v112, 0
	v_mov_b32_e32 v113, 0
	v_mov_b32_e32 v114, 0
	v_mov_b32_e32 v115, 0
	s_and_saveexec_b64 s[0:1], s[10:11]
	s_cbranch_execz .LBB0_1583
	ds_read_b128 v[112:115], v230 offset:2048
	ds_read_b128 v[104:107], v230 offset:2560
	ds_read_b128 v[108:111], v230 offset:3072
	ds_read_b128 v[168:171], v230 offset:3584
.LBB0_1583:
	s_or_b64 exec, exec, s[0:1]
	v_mov_b32_dpp v118, v68 row_shr:1 row_mask:0xf bank_mask:0xf bound_ctrl:1
	v_mov_b32_dpp v120, v76 row_shr:1 row_mask:0xf bank_mask:0xf bound_ctrl:1
	v_mov_b32_dpp v122, v64 row_shr:1 row_mask:0xf bank_mask:0xf bound_ctrl:1
	v_mov_b32_dpp v116, v80 row_shr:1 row_mask:0xf bank_mask:0xf bound_ctrl:1
	v_mov_b32_dpp v117, v81 row_shr:1 row_mask:0xf bank_mask:0xf bound_ctrl:1
	s_waitcnt lgkmcnt(0)
	v_pk_add_f32 v[112:113], v[112:113], v[116:117]
	v_mov_b32_dpp v119, v69 row_shr:1 row_mask:0xf bank_mask:0xf bound_ctrl:1
	v_pk_add_f32 v[108:109], v[108:109], v[118:119]
	v_pk_fma_f32 v[112:113], v[152:153], v[112:113], v[164:165]
	v_pk_fma_f32 v[112:113], v[156:157], v[108:109], v[112:113]
	v_pk_fma_f32 v[112:113], v[96:97], v[160:161], v[112:113]
	v_exp_f32_e32 v116, v112
	v_exp_f32_e32 v117, v113
	v_mov_b32_dpp v121, v77 row_shr:1 row_mask:0xf bank_mask:0xf bound_ctrl:1
	v_mov_b32_dpp v123, v65 row_shr:1 row_mask:0xf bank_mask:0xf bound_ctrl:1
	v_mov_b32_dpp v130, v70 row_shr:1 row_mask:0xf bank_mask:0xf bound_ctrl:1
	v_mov_b32_dpp v134, v78 row_shr:1 row_mask:0xf bank_mask:0xf bound_ctrl:1
	v_mov_b32_dpp v178, v66 row_shr:1 row_mask:0xf bank_mask:0xf bound_ctrl:1
	v_mov_b32_dpp v124, v82 row_shr:1 row_mask:0xf bank_mask:0xf bound_ctrl:1
	v_add_f32_e32 v116, 1.0, v116
	v_add_f32_e32 v117, 1.0, v117
	v_mov_b32_dpp v125, v83 row_shr:1 row_mask:0xf bank_mask:0xf bound_ctrl:1
	v_rcp_f32_e32 v116, v116
	v_rcp_f32_e32 v117, v117
	v_mov_b32_dpp v131, v71 row_shr:1 row_mask:0xf bank_mask:0xf bound_ctrl:1
	v_pk_add_f32 v[114:115], v[114:115], v[124:125]
	v_pk_add_f32 v[110:111], v[110:111], v[130:131]
	v_pk_fma_f32 v[114:115], v[154:155], v[114:115], v[166:167]
	v_pk_fma_f32 v[114:115], v[158:159], v[110:111], v[114:115]
	v_pk_mul_f32 v[112:113], v[112:113], v[116:117]
	v_pk_fma_f32 v[114:115], v[98:99], v[162:163], v[114:115]
	v_pk_add_f32 v[104:105], v[104:105], v[120:121]
	v_exp_f32_e32 v116, v114
	v_exp_f32_e32 v117, v115
	v_pk_add_f32 v[118:119], v[168:169], v[122:123]
	v_add_f32_e32 v116, 1.0, v116
	v_add_f32_e32 v117, 1.0, v117
	v_rcp_f32_e32 v116, v116
	v_rcp_f32_e32 v117, v117
	v_pk_fma_f32 v[104:105], v[136:137], v[104:105], v[148:149]
	v_mov_b32_dpp v135, v79 row_shr:1 row_mask:0xf bank_mask:0xf bound_ctrl:1
	v_pk_fma_f32 v[104:105], v[140:141], v[118:119], v[104:105]
	v_mov_b32_dpp v179, v67 row_shr:1 row_mask:0xf bank_mask:0xf bound_ctrl:1
	v_pk_fma_f32 v[104:105], v[92:93], v[144:145], v[104:105]
	v_pk_add_f32 v[106:107], v[106:107], v[134:135]
	v_pk_mul_f32 v[114:115], v[114:115], v[116:117]
;     __device__ __forceinline__ void run(const f32x4 (&acc)[2][2][4][2], const Unit& u, const Unit& nxt, bool has_next, int ui, int wr, int wc, int fr_in, int fq_in) const {
;     ...
;         for (int n = 0; n < 2; ++n) {
;             const int cl = wc * 32 + n * 16 + 4 * fq, ch = u.pn * 128 + cl;
;             const PG8_LAS float* pp = prm + slot * 1024 + cl;
;             const f32x4 wg0 = *(const PG8_LAS f32x4*)(pp), wg1 = *(const PG8_LAS f32x4*)(pp + 128), wg2 = *(const PG8_LAS f32x4*)(pp + 256), bg = *(const PG8_LAS f32x4*)(pp + 384);
;             const f32x4 wv0 = *(const PG8_LAS f32x4*)(pp + 512), wv1 = *(const PG8_LAS f32x4*)(pp + 640), wv2 = *(const PG8_LAS f32x4*)(pp + 768), bv = *(const PG8_LAS f32x4*)(pp + 896);
; #pragma unroll
;             for (int ai = 0; ai < 2; ++ai) {
;                 const int grp = 2 * ai + wr;
;                 f32x4 hg2 = {0.f, 0.f, 0.f, 0.f}, hg3 = hg2, hv2 = hg2, hv3 = hg2;
;                 if (grp > 0 && fr == 0) { const PG8_LAS float* xp = xr + ((grp - 1) * 2) * 256 + cl;
;                     hg2 = *(const PG8_LAS f32x4*)(xp); hg3 = *(const PG8_LAS f32x4*)(xp + 256); hv2 = *(const PG8_LAS f32x4*)(xp + 128); hv3 = *(const PG8_LAS f32x4*)(xp + 256 + 128); }
;                 f32x4 pg2, pg1, pv2, pv1;
;                 {
;                     const f32x4 g2 = acc[ai][0][2][n] * rs[ai][2], g3 = acc[ai][0][3][n] * rs[ai][3], v2 = acc[ai][1][2][n] * rs[ai][2], v3 = acc[ai][1][3][n] * rs[ai][3];
; #pragma unroll
;                     for (int i = 0; i < 4; ++i) {
;                         float a0 = g2[i], a1 = g3[i], a2 = v2[i], a3 = v3[i];
;                         asm volatile("" : "+v"(a0), "+v"(a1), "+v"(a2), "+v"(a3));
;                         const float t0 = DPPF(a0, 0x111), t1 = DPPF(a1, 0x111), t2 = DPPF(a2, 0x111), t3 = DPPF(a3, 0x111);
;                         pg2[i] = t0 + hg2[i]; pg1[i] = t1 + hg3[i]; pv2[i] = t2 + hv2[i]; pv1[i] = t3 + hv3[i]; }
;                 }
; #pragma unroll
;                 for (int m = 0; m < 4; ++m) {
;                     const f32x4 gc = acc[ai][0][m][n] * rs[ai][m], vc = acc[ai][1][m][n] * rs[ai][m];
;                     const f32x4 cgt = bg + wg0 * pg2 + wg1 * pg1 + wg2 * gc, cvl = bv + wv0 * pv2 + wv1 * pv1 + wv2 * vc;
;                     float a[4];
; #pragma unroll
;                     for (int i = 0; i < 4; ++i) a[i] = cgt[i] * sigmoidf_(cgt[i]) * cvl[i];
	v_mov_b32_e32 v116, v73
	v_pk_fma_f32 v[108:109], v[152:153], v[108:109], v[164:165]
	v_pk_mul_f32 v[104:105], v[104:105], v[112:113]
	v_pk_add_f32 v[112:113], v[170:171], v[178:179]
	v_pk_fma_f32 v[106:107], v[138:139], v[106:107], v[150:151]
	v_pk_fma_f32 v[108:109], v[96:97], v[156:157], v[108:109]
	v_pk_fma_f32 v[106:107], v[142:143], v[112:113], v[106:107]
	v_pk_fma_f32 v[108:109], v[88:89], v[160:161], v[108:109]
	v_pk_fma_f32 v[106:107], v[94:95], v[146:147], v[106:107]
	v_pk_mul_f32 v[106:107], v[106:107], v[114:115]
	v_exp_f32_e32 v117, v108
	v_exp_f32_e32 v120, v109
	v_add_u32_e32 v177, 0x80, v231
	v_cvt_pk_bf16_f32 v104, v104, v105
	v_cvt_pk_bf16_f32 v105, v106, v107
	v_mov_b64_e32 v[106:107], s[16:17]
	v_mad_i64_i32 v[122:123], s[0:1], v177, s73, v[106:107]
	v_lshl_add_u64 v[114:115], v[122:123], 0, v[174:175]
	global_store_dwordx2 v[114:115], v[104:105], off
	v_add_f32_e32 v104, 1.0, v117
	v_add_f32_e32 v105, 1.0, v120
	v_rcp_f32_e32 v104, v104
	v_rcp_f32_e32 v105, v105
	v_pk_fma_f32 v[96:97], v[96:97], v[152:153], v[164:165]
	v_pk_mul_f32 v[104:105], v[108:109], v[104:105]
	v_pk_fma_f32 v[108:109], v[154:155], v[110:111], v[166:167]
	v_pk_fma_f32 v[108:109], v[98:99], v[158:159], v[108:109]
	v_pk_fma_f32 v[108:109], v[90:91], v[162:163], v[108:109]
	v_pk_fma_f32 v[96:97], v[88:89], v[156:157], v[96:97]
	v_exp_f32_e32 v114, v108
	v_exp_f32_e32 v115, v109
	v_pk_fma_f32 v[110:111], v[136:137], v[118:119], v[148:149]
	v_add_f32_e32 v114, 1.0, v114
	v_rcp_f32_e32 v114, v114
	v_add_f32_e32 v115, 1.0, v115
	v_rcp_f32_e32 v115, v115
	v_pk_fma_f32 v[110:111], v[92:93], v[140:141], v[110:111]
	v_pk_fma_f32 v[96:97], v[80:81], v[160:161], v[96:97]
	v_pk_fma_f32 v[110:111], v[84:85], v[144:145], v[110:111]
	v_pk_mul_f32 v[108:109], v[108:109], v[114:115]
	v_pk_mul_f32 v[104:105], v[110:111], v[104:105]
	v_pk_fma_f32 v[110:111], v[138:139], v[112:113], v[150:151]
	v_cvt_pk_bf16_f32 v104, v104, v105
	v_pk_fma_f32 v[110:111], v[94:95], v[142:143], v[110:111]
	v_pk_fma_f32 v[98:99], v[98:99], v[154:155], v[166:167]
	v_pk_fma_f32 v[110:111], v[86:87], v[146:147], v[110:111]
	v_pk_mul_f32 v[108:109], v[110:111], v[108:109]
	v_exp_f32_e32 v110, v96
	v_exp_f32_e32 v111, v97
	v_cvt_pk_bf16_f32 v105, v108, v109
	v_add_u32_e32 v108, 0x81, v231
	v_mad_i64_i32 v[124:125], s[0:1], v108, s73, v[106:107]
	v_lshl_add_u64 v[108:109], v[124:125], 0, v[174:175]
	global_store_dwordx2 v[108:109], v[104:105], off
	v_add_f32_e32 v104, 1.0, v110
	v_add_f32_e32 v105, 1.0, v111
	v_rcp_f32_e32 v104, v104
	v_rcp_f32_e32 v105, v105
	v_pk_fma_f32 v[98:99], v[90:91], v[158:159], v[98:99]
	v_pk_fma_f32 v[92:93], v[92:93], v[136:137], v[148:149]
	v_pk_fma_f32 v[98:99], v[82:83], v[162:163], v[98:99]
	v_pk_mul_f32 v[96:97], v[96:97], v[104:105]
	v_exp_f32_e32 v104, v98
	v_exp_f32_e32 v105, v99
	v_pk_fma_f32 v[92:93], v[84:85], v[140:141], v[92:93]
	v_add_f32_e32 v104, 1.0, v104
	v_add_f32_e32 v105, 1.0, v105
	v_rcp_f32_e32 v104, v104
	v_rcp_f32_e32 v105, v105
	v_pk_fma_f32 v[94:95], v[94:95], v[138:139], v[150:151]
	v_pk_fma_f32 v[92:93], v[76:77], v[144:145], v[92:93]
	v_pk_fma_f32 v[94:95], v[86:87], v[142:143], v[94:95]
	v_pk_mul_f32 v[92:93], v[92:93], v[96:97]
	v_pk_mul_f32 v[96:97], v[98:99], v[104:105]
	v_pk_fma_f32 v[94:95], v[78:79], v[146:147], v[94:95]
	v_pk_fma_f32 v[88:89], v[152:153], v[88:89], v[164:165]
	v_pk_mul_f32 v[94:95], v[94:95], v[96:97]
	v_mov_b32_e32 v96, v75
	v_pk_fma_f32 v[80:81], v[156:157], v[80:81], v[88:89]
	v_pk_fma_f32 v[68:69], v[160:161], v[68:69], v[80:81]
	v_exp_f32_e32 v80, v68
	v_exp_f32_e32 v81, v69
	v_cvt_pk_bf16_f32 v92, v92, v93
	v_add_f32_e32 v80, 1.0, v80
	v_add_f32_e32 v81, 1.0, v81
	v_rcp_f32_e32 v80, v80
	v_rcp_f32_e32 v81, v81
	v_cvt_pk_bf16_f32 v93, v94, v95
	v_add_u32_e32 v94, 0x82, v231
	v_mad_i64_i32 v[130:131], s[0:1], v94, s73, v[106:107]
	v_pk_mul_f32 v[68:69], v[68:69], v[80:81]
	v_pk_fma_f32 v[80:81], v[154:155], v[90:91], v[166:167]
	v_lshl_add_u64 v[94:95], v[130:131], 0, v[174:175]
	v_pk_fma_f32 v[80:81], v[158:159], v[82:83], v[80:81]
	global_store_dwordx2 v[94:95], v[92:93], off
	v_pk_fma_f32 v[70:71], v[162:163], v[70:71], v[80:81]
	v_add_u32_e32 v176, 16, v202
	v_exp_f32_e32 v82, v70
	v_exp_f32_e32 v83, v71
	v_pk_fma_f32 v[80:81], v[84:85], v[136:137], v[148:149]
	v_add_f32_e32 v82, 1.0, v82
	v_rcp_f32_e32 v82, v82
	v_add_f32_e32 v83, 1.0, v83
	v_rcp_f32_e32 v83, v83
	v_pk_fma_f32 v[76:77], v[76:77], v[140:141], v[80:81]
	v_mov_b32_e32 v104, 0
	v_pk_fma_f32 v[64:65], v[64:65], v[144:145], v[76:77]
	v_mov_b32_e32 v108, 0
	v_pk_mul_f32 v[64:65], v[64:65], v[68:69]
	v_pk_mul_f32 v[68:69], v[70:71], v[82:83]
	v_pk_fma_f32 v[70:71], v[86:87], v[138:139], v[150:151]
	v_cvt_pk_bf16_f32 v64, v64, v65
	v_pk_fma_f32 v[70:71], v[78:79], v[142:143], v[70:71]
	v_mov_b32_e32 v109, 0
	v_pk_fma_f32 v[66:67], v[66:67], v[146:147], v[70:71]
	v_mov_b32_e32 v110, 0
	v_pk_mul_f32 v[66:67], v[66:67], v[68:69]
	v_mov_b32_e32 v111, 0
	v_cvt_pk_bf16_f32 v65, v66, v67
	v_add_u32_e32 v66, 0x83, v231
	v_mad_i64_i32 v[134:135], s[0:1], v66, s73, v[106:107]
	v_lshl_add_u64 v[66:67], v[134:135], 0, v[174:175]
	global_store_dwordx2 v[66:67], v[64:65], off
	ds_read_b128 v[84:87], v203 offset:64
	ds_read_b128 v[88:91], v203 offset:576
	ds_read_b128 v[92:95], v203 offset:1088
	ds_read_b128 v[96:99], v203 offset:1600
	ds_read_b128 v[64:67], v203 offset:2112
	ds_read_b128 v[68:71], v203 offset:2624
	ds_read_b128 v[76:79], v203 offset:3136
	ds_read_b128 v[80:83], v203 offset:3648
	v_mov_b32_e32 v106, 0
	v_mov_b32_e32 v107, 0
	v_mov_b32_e32 v112, 0
	v_mov_b32_e32 v113, 0
	v_mov_b32_e32 v114, 0
	v_mov_b32_e32 v115, 0
	v_mov_b32_e32 v116, 0
	v_mov_b32_e32 v117, 0
	v_mov_b32_e32 v118, 0
	v_mov_b32_e32 v119, 0
	v_mov_b32_e32 v120, 0
	v_mov_b32_e32 v121, 0
	s_and_saveexec_b64 s[0:1], s[4:5]
	s_cbranch_execz .LBB0_1585
	v_lshl_add_u32 v105, v176, 2, s69
	ds_read_b128 v[118:121], v105
	ds_read_b128 v[110:113], v105 offset:512
	ds_read_b128 v[114:117], v105 offset:1024
	ds_read_b128 v[106:109], v105 offset:1536
;     __device__ __forceinline__ void run(const f32x4 (&acc)[2][2][4][2], const Unit& u, const Unit& nxt, bool has_next, int ui, int wr, int wc, int fr_in, int fq_in) const {
;     ...
;         for (int n = 0; n < 2; ++n) {
;             const int cl = wc * 32 + n * 16 + 4 * fq, ch = u.pn * 128 + cl;
;             const PG8_LAS float* pp = prm + slot * 1024 + cl;
;             const f32x4 wg0 = *(const PG8_LAS f32x4*)(pp), wg1 = *(const PG8_LAS f32x4*)(pp + 128), wg2 = *(const PG8_LAS f32x4*)(pp + 256), bg = *(const PG8_LAS f32x4*)(pp + 384);
;             const f32x4 wv0 = *(const PG8_LAS f32x4*)(pp + 512), wv1 = *(const PG8_LAS f32x4*)(pp + 640), wv2 = *(const PG8_LAS f32x4*)(pp + 768), bv = *(const PG8_LAS f32x4*)(pp + 896);
; #pragma unroll
;             for (int ai = 0; ai < 2; ++ai) {
;                 const int grp = 2 * ai + wr;
;                 f32x4 hg2 = {0.f, 0.f, 0.f, 0.f}, hg3 = hg2, hv2 = hg2, hv3 = hg2;
;                 if (grp > 0 && fr == 0) { const PG8_LAS float* xp = xr + ((grp - 1) * 2) * 256 + cl;
;                     hg2 = *(const PG8_LAS f32x4*)(xp); hg3 = *(const PG8_LAS f32x4*)(xp + 256); hv2 = *(const PG8_LAS f32x4*)(xp + 128); hv3 = *(const PG8_LAS f32x4*)(xp + 256 + 128); }
;                 f32x4 pg2, pg1, pv2, pv1;
;                 {
;                     const f32x4 g2 = acc[ai][0][2][n] * rs[ai][2], g3 = acc[ai][0][3][n] * rs[ai][3], v2 = acc[ai][1][2][n] * rs[ai][2], v3 = acc[ai][1][3][n] * rs[ai][3];
; #pragma unroll
;                     for (int i = 0; i < 4; ++i) {
;                         float a0 = g2[i], a1 = g3[i], a2 = v2[i], a3 = v3[i];
;                         asm volatile("" : "+v"(a0), "+v"(a1), "+v"(a2), "+v"(a3));
;                         const float t0 = DPPF(a0, 0x111), t1 = DPPF(a1, 0x111), t2 = DPPF(a2, 0x111), t3 = DPPF(a3, 0x111);
;                         pg2[i] = t0 + hg2[i]; pg1[i] = t1 + hg3[i]; pv2[i] = t2 + hv2[i]; pv1[i] = t3 + hv3[i]; }
;                 }
; #pragma unroll
;                 for (int m = 0; m < 4; ++m) {
;                     const f32x4 gc = acc[ai][0][m][n] * rs[ai][m], vc = acc[ai][1][m][n] * rs[ai][m];
;                     const f32x4 cgt = bg + wg0 * pg2 + wg1 * pg1 + wg2 * gc, cvl = bv + wv0 * pv2 + wv1 * pv1 + wv2 * vc;
;                     float a[4];
; #pragma unroll
;                     for (int i = 0; i < 4; ++i) a[i] = cgt[i] * sigmoidf_(cgt[i]) * cvl[i];
.LBB0_1585:
	s_or_b64 exec, exec, s[0:1]
	v_mov_b32_dpp v146, v44 row_shr:1 row_mask:0xf bank_mask:0xf bound_ctrl:1
	s_nop 0
	v_mov_b32_dpp v152, v32 row_shr:1 row_mask:0xf bank_mask:0xf bound_ctrl:1
	v_mov_b32_dpp v150, v40 row_shr:1 row_mask:0xf bank_mask:0xf bound_ctrl:1
	v_mov_b32_dpp v148, v36 row_shr:1 row_mask:0xf bank_mask:0xf bound_ctrl:1
	v_mov_b32_dpp v149, v37 row_shr:1 row_mask:0xf bank_mask:0xf bound_ctrl:1
	v_mov_b32_dpp v147, v45 row_shr:1 row_mask:0xf bank_mask:0xf bound_ctrl:1
	v_mov_b32_dpp v151, v41 row_shr:1 row_mask:0xf bank_mask:0xf bound_ctrl:1
	v_mov_b32_dpp v153, v33 row_shr:1 row_mask:0xf bank_mask:0xf bound_ctrl:1
	v_mov_b32_dpp v154, v46 row_shr:1 row_mask:0xf bank_mask:0xf bound_ctrl:1
	v_mov_b32_dpp v160, v34 row_shr:1 row_mask:0xf bank_mask:0xf bound_ctrl:1
	s_waitcnt lgkmcnt(0)
	v_pk_add_f32 v[118:119], v[118:119], v[146:147]
	v_mov_b32_e32 v140, v100
	v_mov_b32_e32 v141, v100
	v_mov_b32_dpp v158, v42 row_shr:1 row_mask:0xf bank_mask:0xf bound_ctrl:1
	v_pk_add_f32 v[114:115], v[114:115], v[148:149]
	v_pk_fma_f32 v[118:119], v[84:85], v[118:119], v[96:97]
	v_mov_b32_dpp v157, v39 row_shr:1 row_mask:0xf bank_mask:0xf bound_ctrl:1
	v_pk_fma_f32 v[118:119], v[88:89], v[114:115], v[118:119]
	v_mov_b32_dpp v159, v43 row_shr:1 row_mask:0xf bank_mask:0xf bound_ctrl:1
	v_pk_fma_f32 v[118:119], v[60:61], v[92:93], v[118:119]
	v_mov_b32_dpp v156, v38 row_shr:1 row_mask:0xf bank_mask:0xf bound_ctrl:1
	v_mov_b32_dpp v161, v35 row_shr:1 row_mask:0xf bank_mask:0xf bound_ctrl:1
	v_mov_b32_e32 v162, v100
	v_mov_b32_e32 v163, v100
	v_mov_b32_dpp v155, v47 row_shr:1 row_mask:0xf bank_mask:0xf bound_ctrl:1
	v_exp_f32_e32 v100, v118
	v_exp_f32_e32 v105, v119
	v_mov_b64_e32 v[140:141], v[56:57]
	v_add_f32_e32 v100, 1.0, v100
	v_rcp_f32_e32 v146, v100
	v_add_f32_e32 v100, 1.0, v105
	v_rcp_f32_e32 v147, v100
	v_pk_add_f32 v[56:57], v[110:111], v[150:151]
	v_pk_add_f32 v[116:117], v[116:117], v[156:157]
	v_pk_mul_f32 v[110:111], v[118:119], v[146:147]
	v_pk_add_f32 v[118:119], v[120:121], v[154:155]
	v_pk_add_f32 v[106:107], v[106:107], v[152:153]
	v_pk_fma_f32 v[118:119], v[86:87], v[118:119], v[98:99]
	v_pk_fma_f32 v[56:57], v[64:65], v[56:57], v[80:81]
	v_pk_fma_f32 v[118:119], v[90:91], v[116:117], v[118:119]
	v_pk_fma_f32 v[56:57], v[68:69], v[106:107], v[56:57]
	v_pk_fma_f32 v[118:119], v[62:63], v[94:95], v[118:119]
	v_pk_fma_f32 v[56:57], v[140:141], v[76:77], v[56:57]
	v_exp_f32_e32 v100, v118
	v_exp_f32_e32 v105, v119
	v_pk_mul_f32 v[56:57], v[56:57], v[110:111]
	v_add_f32_e32 v100, 1.0, v100
	v_rcp_f32_e32 v120, v100
	v_add_f32_e32 v100, 1.0, v105
	v_rcp_f32_e32 v121, v100
	v_pk_add_f32 v[110:111], v[112:113], v[158:159]
	v_pk_add_f32 v[108:109], v[108:109], v[160:161]
	v_pk_fma_f32 v[110:111], v[66:67], v[110:111], v[82:83]
	v_add_u32_e32 v144, s12, v176
	v_pk_fma_f32 v[110:111], v[70:71], v[108:109], v[110:111]
	v_ashrrev_i32_e32 v145, 31, v144
	v_pk_mul_f32 v[112:113], v[118:119], v[120:121]
	v_pk_fma_f32 v[110:111], v[58:59], v[78:79], v[110:111]
	v_mov_b32_e32 v142, v101
	v_pk_mul_f32 v[110:111], v[110:111], v[112:113]
	v_cvt_pk_bf16_f32 v112, v56, v57
	v_lshlrev_b64 v[56:57], 1, v[144:145]
	v_cvt_pk_bf16_f32 v113, v110, v111
	v_lshl_add_u64 v[110:111], v[128:129], 0, v[56:57]
	v_mov_b32_e32 v143, v101
	global_store_dwordx2 v[110:111], v[112:113], off
	v_pk_fma_f32 v[110:111], v[84:85], v[114:115], v[96:97]
	v_pk_fma_f32 v[110:111], v[60:61], v[88:89], v[110:111]
	v_pk_fma_f32 v[106:107], v[64:65], v[106:107], v[80:81]
	v_pk_fma_f32 v[110:111], v[52:53], v[92:93], v[110:111]
	v_exp_f32_e32 v105, v110
	v_exp_f32_e32 v113, v111
	v_mov_b32_e32 v100, v101
	v_add_f32_e32 v105, 1.0, v105
	v_rcp_f32_e32 v112, v105
	v_add_f32_e32 v105, 1.0, v113
	v_rcp_f32_e32 v113, v105
	v_pk_fma_f32 v[106:107], v[140:141], v[68:69], v[106:107]
	v_pk_mul_f32 v[100:101], v[110:111], v[112:113]
	v_pk_fma_f32 v[110:111], v[86:87], v[116:117], v[98:99]
	v_pk_fma_f32 v[108:109], v[66:67], v[108:109], v[82:83]
	v_pk_fma_f32 v[110:111], v[62:63], v[90:91], v[110:111]
	v_pk_fma_f32 v[106:107], v[48:49], v[76:77], v[106:107]
	v_pk_fma_f32 v[110:111], v[54:55], v[94:95], v[110:111]
	v_pk_fma_f32 v[108:109], v[58:59], v[70:71], v[108:109]
	v_exp_f32_e32 v105, v110
	v_exp_f32_e32 v113, v111
	v_mov_b32_e32 v138, v102
	v_add_f32_e32 v105, 1.0, v105
	v_rcp_f32_e32 v112, v105
	v_add_f32_e32 v105, 1.0, v113
	v_rcp_f32_e32 v113, v105
	v_mov_b32_e32 v139, v102
	v_pk_mul_f32 v[100:101], v[106:107], v[100:101]
	v_pk_fma_f32 v[108:109], v[50:51], v[78:79], v[108:109]
	v_pk_mul_f32 v[106:107], v[110:111], v[112:113]
	v_pk_fma_f32 v[60:61], v[60:61], v[84:85], v[96:97]
	v_pk_mul_f32 v[106:107], v[108:109], v[106:107]
	v_pk_fma_f32 v[60:61], v[52:53], v[88:89], v[60:61]
	v_cvt_pk_bf16_f32 v100, v100, v101
	v_cvt_pk_bf16_f32 v101, v106, v107
	v_lshl_add_u64 v[106:107], v[126:127], 0, v[56:57]
	v_pk_fma_f32 v[60:61], v[44:45], v[92:93], v[60:61]
	v_mov_b32_e32 v136, v103
	v_mov_b32_e32 v137, v103
	global_store_dwordx2 v[106:107], v[100:101], off
	v_pk_fma_f32 v[52:53], v[52:53], v[84:85], v[96:97]
	v_exp_f32_e32 v105, v60
	v_pk_fma_f32 v[44:45], v[44:45], v[88:89], v[52:53]
	v_exp_f32_e32 v107, v61
	v_pk_fma_f32 v[36:37], v[36:37], v[92:93], v[44:45]
	v_mov_b32_e32 v100, v102
	v_mov_b32_e32 v101, v102
	v_pk_fma_f32 v[62:63], v[62:63], v[86:87], v[98:99]
	v_pk_fma_f32 v[62:63], v[54:55], v[90:91], v[62:63]
	v_exp_f32_e32 v44, v36
	v_exp_f32_e32 v45, v37
	v_add_f32_e32 v102, 1.0, v105
	v_pk_fma_f32 v[62:63], v[46:47], v[94:95], v[62:63]
	v_rcp_f32_e32 v106, v102
	v_add_f32_e32 v102, 1.0, v107
	v_rcp_f32_e32 v107, v102
	v_exp_f32_e32 v102, v62
	v_exp_f32_e32 v105, v63
; __device__ __forceinline__ unsigned pk2(float lo, float hi) { f32x2_t v = {lo, hi}; bf16x2_t b = __builtin_convertvector(v, bf16x2_t); return __builtin_bit_cast(unsigned, b); }
; #define DPPF(v, ctrl) __builtin_bit_cast(float, __builtin_amdgcn_update_dpp(0, __builtin_bit_cast(int, (v)), (ctrl), 0xf, 0xf, false))
;     __device__ __forceinline__ void run(const f32x4 (&acc)[2][2][4][2], const Unit& u, const Unit& nxt, bool has_next, int ui, int wr, int wc, int fr_in, int fq_in) const {
;     ...
;             for (int ai = 0; ai < 2; ++ai) {
;                 const int grp = 2 * ai + wr;
;                 f32x4 hg2 = {0.f, 0.f, 0.f, 0.f}, hg3 = hg2, hv2 = hg2, hv3 = hg2;
;                 if (grp > 0 && fr == 0) { const PG8_LAS float* xp = xr + ((grp - 1) * 2) * 256 + cl;
;                     hg2 = *(const PG8_LAS f32x4*)(xp); hg3 = *(const PG8_LAS f32x4*)(xp + 256); hv2 = *(const PG8_LAS f32x4*)(xp + 128); hv3 = *(const PG8_LAS f32x4*)(xp + 256 + 128); }
;                 f32x4 pg2, pg1, pv2, pv1;
;                 {
;                     const f32x4 g2 = acc[ai][0][2][n] * rs[ai][2], g3 = acc[ai][0][3][n] * rs[ai][3], v2 = acc[ai][1][2][n] * rs[ai][2], v3 = acc[ai][1][3][n] * rs[ai][3];
; #pragma unroll
;                     for (int i = 0; i < 4; ++i) {
;                         float a0 = g2[i], a1 = g3[i], a2 = v2[i], a3 = v3[i];
;                         asm volatile("" : "+v"(a0), "+v"(a1), "+v"(a2), "+v"(a3));
;                         const float t0 = DPPF(a0, 0x111), t1 = DPPF(a1, 0x111), t2 = DPPF(a2, 0x111), t3 = DPPF(a3, 0x111);
;                         pg2[i] = t0 + hg2[i]; pg1[i] = t1 + hg3[i]; pv2[i] = t2 + hv2[i]; pv1[i] = t3 + hv3[i]; }
;                 }
; #pragma unroll
;                 for (int m = 0; m < 4; ++m) {
;                     const f32x4 gc = acc[ai][0][m][n] * rs[ai][m], vc = acc[ai][1][m][n] * rs[ai][m];
;                     const f32x4 cgt = bg + wg0 * pg2 + wg1 * pg1 + wg2 * gc, cvl = bv + wv0 * pv2 + wv1 * pv1 + wv2 * vc;
;                     float a[4];
; #pragma unroll
;                     for (int i = 0; i < 4; ++i) a[i] = cgt[i] * sigmoidf_(cgt[i]) * cvl[i];
;                     u32x2 w; w.x = pk2(a[0], a[1]); w.y = pk2(a[2], a[3]);
;                     *(u32x2*)(A + (size_t)(u.pm * BM + ai * 128 + wr * 64 + 4 * fr + m) * DFF + ch) = w;
;                     pg2 = pg1; pg1 = gc; pv2 = pv1; pv1 = vc;
	v_add_f32_e32 v44, 1.0, v44
	v_add_f32_e32 v45, 1.0, v45
	v_rcp_f32_e32 v44, v44
	v_rcp_f32_e32 v45, v45
	v_add_f32_e32 v102, 1.0, v102
	v_pk_mul_f32 v[60:61], v[60:61], v[106:107]
	v_rcp_f32_e32 v106, v102
	v_add_f32_e32 v102, 1.0, v105
	v_rcp_f32_e32 v107, v102
	v_mov_b32_e32 v102, v103
	v_pk_mul_f32 v[36:37], v[36:37], v[44:45]
	v_pk_fma_f32 v[44:45], v[54:55], v[86:87], v[98:99]
	v_pk_fma_f32 v[44:45], v[46:47], v[90:91], v[44:45]
	v_pk_fma_f32 v[100:101], v[140:141], v[64:65], v[80:81]
	v_pk_fma_f32 v[38:39], v[38:39], v[94:95], v[44:45]
	v_exp_f32_e32 v46, v38
	v_exp_f32_e32 v47, v39
	v_pk_fma_f32 v[100:101], v[48:49], v[68:69], v[100:101]
	v_add_f32_e32 v46, 1.0, v46
	v_rcp_f32_e32 v46, v46
	v_add_f32_e32 v47, 1.0, v47
	v_rcp_f32_e32 v47, v47
	v_pk_fma_f32 v[44:45], v[48:49], v[64:65], v[80:81]
	v_pk_fma_f32 v[100:101], v[40:41], v[76:77], v[100:101]
	v_pk_fma_f32 v[40:41], v[40:41], v[68:69], v[44:45]
	v_pk_fma_f32 v[58:59], v[58:59], v[66:67], v[82:83]
	v_pk_fma_f32 v[32:33], v[32:33], v[76:77], v[40:41]
	v_pk_fma_f32 v[58:59], v[50:51], v[70:71], v[58:59]
	v_pk_mul_f32 v[32:33], v[32:33], v[36:37]
	v_pk_mul_f32 v[36:37], v[38:39], v[46:47]
	v_pk_fma_f32 v[38:39], v[50:51], v[66:67], v[82:83]
	v_pk_fma_f32 v[38:39], v[42:43], v[70:71], v[38:39]
	v_pk_mul_f32 v[62:63], v[62:63], v[106:107]
	v_pk_fma_f32 v[58:59], v[42:43], v[78:79], v[58:59]
	v_pk_fma_f32 v[34:35], v[34:35], v[78:79], v[38:39]
	v_pk_mul_f32 v[60:61], v[100:101], v[60:61]
	v_pk_mul_f32 v[58:59], v[58:59], v[62:63]
	v_pk_mul_f32 v[34:35], v[34:35], v[36:37]
	v_cvt_pk_bf16_f32 v60, v60, v61
	v_cvt_pk_bf16_f32 v61, v58, v59
	v_lshl_add_u64 v[58:59], v[132:133], 0, v[56:57]
	v_cvt_pk_bf16_f32 v32, v32, v33
	v_cvt_pk_bf16_f32 v33, v34, v35
	v_lshl_add_u64 v[34:35], v[172:173], 0, v[56:57]
	global_store_dwordx2 v[58:59], v[60:61], off
	global_store_dwordx2 v[34:35], v[32:33], off
	v_mov_b32_e32 v105, 0
	v_mov_b32_e32 v106, 0
	v_mov_b32_e32 v107, 0
	v_mov_b32_e32 v32, 0
	v_mov_b32_e32 v33, 0
	v_mov_b32_e32 v34, 0
	v_mov_b32_e32 v35, 0
	v_mov_b32_e32 v36, 0
	v_mov_b32_e32 v37, 0
	v_mov_b32_e32 v38, 0
	v_mov_b32_e32 v39, 0
	v_mov_b32_e32 v40, 0
	v_mov_b32_e32 v41, 0
	v_mov_b32_e32 v42, 0
	v_mov_b32_e32 v43, 0
	s_and_saveexec_b64 s[0:1], s[10:11]
	s_cbranch_execz .LBB0_1587
	ds_read_b128 v[40:43], v230 offset:2112
	ds_read_b128 v[32:35], v230 offset:2624
	ds_read_b128 v[36:39], v230 offset:3136
	ds_read_b128 v[104:107], v230 offset:3648
.LBB0_1587:
	s_or_b64 exec, exec, s[0:1]
	v_mov_b32_dpp v54, v4 row_shr:1 row_mask:0xf bank_mask:0xf bound_ctrl:1
	v_mov_b32_dpp v58, v8 row_shr:1 row_mask:0xf bank_mask:0xf bound_ctrl:1
	v_mov_b32_dpp v60, v0 row_shr:1 row_mask:0xf bank_mask:0xf bound_ctrl:1
	v_mov_b32_dpp v52, v12 row_shr:1 row_mask:0xf bank_mask:0xf bound_ctrl:1
	v_mov_b32_dpp v53, v13 row_shr:1 row_mask:0xf bank_mask:0xf bound_ctrl:1
	s_waitcnt lgkmcnt(0)
;     __device__ __forceinline__ void run(const f32x4 (&acc)[2][2][4][2], const Unit& u, const Unit& nxt, bool has_next, int ui, int wr, int wc, int fr_in, int fq_in) const {
;     ...
;             for (int ai = 0; ai < 2; ++ai) {
;                 const int grp = 2 * ai + wr;
;                 f32x4 hg2 = {0.f, 0.f, 0.f, 0.f}, hg3 = hg2, hv2 = hg2, hv3 = hg2;
;                 if (grp > 0 && fr == 0) { const PG8_LAS float* xp = xr + ((grp - 1) * 2) * 256 + cl;
;                     hg2 = *(const PG8_LAS f32x4*)(xp); hg3 = *(const PG8_LAS f32x4*)(xp + 256); hv2 = *(const PG8_LAS f32x4*)(xp + 128); hv3 = *(const PG8_LAS f32x4*)(xp + 256 + 128); }
;                 f32x4 pg2, pg1, pv2, pv1;
;                 {
;                     const f32x4 g2 = acc[ai][0][2][n] * rs[ai][2], g3 = acc[ai][0][3][n] * rs[ai][3], v2 = acc[ai][1][2][n] * rs[ai][2], v3 = acc[ai][1][3][n] * rs[ai][3];
; #pragma unroll
;                     for (int i = 0; i < 4; ++i) {
;                         float a0 = g2[i], a1 = g3[i], a2 = v2[i], a3 = v3[i];
;                         asm volatile("" : "+v"(a0), "+v"(a1), "+v"(a2), "+v"(a3));
;                         const float t0 = DPPF(a0, 0x111), t1 = DPPF(a1, 0x111), t2 = DPPF(a2, 0x111), t3 = DPPF(a3, 0x111);
;                         pg2[i] = t0 + hg2[i]; pg1[i] = t1 + hg3[i]; pv2[i] = t2 + hv2[i]; pv1[i] = t3 + hv3[i]; }
;                 }
; #pragma unroll
;                 for (int m = 0; m < 4; ++m) {
;                     const f32x4 gc = acc[ai][0][m][n] * rs[ai][m], vc = acc[ai][1][m][n] * rs[ai][m];
;                     const f32x4 cgt = bg + wg0 * pg2 + wg1 * pg1 + wg2 * gc, cvl = bv + wv0 * pv2 + wv1 * pv1 + wv2 * vc;
;                     float a[4];
; #pragma unroll
;                     for (int i = 0; i < 4; ++i) a[i] = cgt[i] * sigmoidf_(cgt[i]) * cvl[i];
;                     u32x2 w; w.x = pk2(a[0], a[1]); w.y = pk2(a[2], a[3]);
;                     *(u32x2*)(A + (size_t)(u.pm * BM + ai * 128 + wr * 64 + 4 * fr + m) * DFF + ch) = w;
;                     pg2 = pg1; pg1 = gc; pv2 = pv1; pv1 = vc;
;                 }
;                 asm volatile("" ::: "memory");
;             }
;         }
;         if (has_next) {
;             prm[(slot ^ 1) * 1024 + tid] = nx0; prm[(slot ^ 1) * 1024 + tid + 512] = nx1;
;             if (tid < 256) rsd[(slot ^ 1) * 256 + tid] = fast_rsq(nrs * (1.0f / DM) + EPS);
;         }
	v_pk_add_f32 v[40:41], v[40:41], v[52:53]
	v_mov_b32_dpp v55, v5 row_shr:1 row_mask:0xf bank_mask:0xf bound_ctrl:1
	v_pk_add_f32 v[36:37], v[36:37], v[54:55]
	v_pk_fma_f32 v[40:41], v[84:85], v[40:41], v[96:97]
	v_pk_fma_f32 v[40:41], v[88:89], v[36:37], v[40:41]
	v_pk_fma_f32 v[40:41], v[28:29], v[92:93], v[40:41]
	v_mov_b32_dpp v59, v9 row_shr:1 row_mask:0xf bank_mask:0xf bound_ctrl:1
	v_exp_f32_e32 v52, v40
	v_exp_f32_e32 v53, v41
	v_mov_b32_dpp v61, v1 row_shr:1 row_mask:0xf bank_mask:0xf bound_ctrl:1
	v_mov_b32_dpp v100, v6 row_shr:1 row_mask:0xf bank_mask:0xf bound_ctrl:1
	v_mov_b32_dpp v102, v10 row_shr:1 row_mask:0xf bank_mask:0xf bound_ctrl:1
	v_mov_b32_dpp v108, v2 row_shr:1 row_mask:0xf bank_mask:0xf bound_ctrl:1
	v_mov_b32_dpp v62, v14 row_shr:1 row_mask:0xf bank_mask:0xf bound_ctrl:1
	v_add_f32_e32 v52, 1.0, v52
	v_add_f32_e32 v53, 1.0, v53
	v_mov_b32_dpp v63, v15 row_shr:1 row_mask:0xf bank_mask:0xf bound_ctrl:1
	v_rcp_f32_e32 v52, v52
	v_rcp_f32_e32 v53, v53
	v_mov_b32_dpp v101, v7 row_shr:1 row_mask:0xf bank_mask:0xf bound_ctrl:1
	v_pk_add_f32 v[42:43], v[42:43], v[62:63]
	v_mov_b32_e32 v111, v72
	v_mov_b32_dpp v103, v11 row_shr:1 row_mask:0xf bank_mask:0xf bound_ctrl:1
	v_pk_add_f32 v[38:39], v[38:39], v[100:101]
	v_pk_fma_f32 v[42:43], v[86:87], v[42:43], v[98:99]
	v_mov_b32_dpp v109, v3 row_shr:1 row_mask:0xf bank_mask:0xf bound_ctrl:1
	v_mov_b32_e32 v110, v72
	v_pk_fma_f32 v[42:43], v[90:91], v[38:39], v[42:43]
	v_pk_mul_f32 v[40:41], v[40:41], v[52:53]
	v_pk_fma_f32 v[42:43], v[30:31], v[94:95], v[42:43]
	v_pk_add_f32 v[32:33], v[32:33], v[58:59]
	v_exp_f32_e32 v52, v42
	v_exp_f32_e32 v53, v43
	v_pk_add_f32 v[48:49], v[104:105], v[60:61]
	v_pk_fma_f32 v[32:33], v[64:65], v[32:33], v[80:81]
	v_add_f32_e32 v52, 1.0, v52
	v_add_f32_e32 v53, 1.0, v53
	v_pk_fma_f32 v[32:33], v[68:69], v[48:49], v[32:33]
	v_rcp_f32_e32 v52, v52
	v_rcp_f32_e32 v53, v53
	v_pk_fma_f32 v[32:33], v[24:25], v[76:77], v[32:33]
	v_pk_add_f32 v[34:35], v[34:35], v[102:103]
	v_pk_mul_f32 v[32:33], v[32:33], v[40:41]
	v_pk_add_f32 v[40:41], v[106:107], v[108:109]
	v_pk_fma_f32 v[34:35], v[66:67], v[34:35], v[82:83]
	v_pk_fma_f32 v[34:35], v[70:71], v[40:41], v[34:35]
	v_pk_mul_f32 v[42:43], v[42:43], v[52:53]
	v_pk_fma_f32 v[34:35], v[26:27], v[78:79], v[34:35]
	v_cvt_pk_bf16_f32 v32, v32, v33
	v_pk_mul_f32 v[34:35], v[34:35], v[42:43]
	v_mov_b32_e32 v50, v73
	v_cvt_pk_bf16_f32 v33, v34, v35
	v_lshl_add_u64 v[34:35], v[122:123], 0, v[56:57]
	v_mov_b32_e32 v51, v73
	global_store_dwordx2 v[34:35], v[32:33], off
	v_pk_fma_f32 v[32:33], v[84:85], v[36:37], v[96:97]
	v_pk_fma_f32 v[32:33], v[28:29], v[88:89], v[32:33]
	v_mov_b32_e32 v72, v73
	v_pk_fma_f32 v[32:33], v[20:21], v[92:93], v[32:33]
	v_exp_f32_e32 v34, v32
	v_exp_f32_e32 v35, v33
	v_mov_b32_e32 v46, v74
	v_mov_b32_e32 v47, v74
	v_add_f32_e32 v34, 1.0, v34
	v_add_f32_e32 v35, 1.0, v35
	v_rcp_f32_e32 v34, v34
	v_rcp_f32_e32 v35, v35
	v_pk_fma_f32 v[28:29], v[28:29], v[84:85], v[96:97]
	v_mov_b32_e32 v44, v75
	v_mov_b32_e32 v45, v75
	v_pk_mul_f32 v[32:33], v[32:33], v[34:35]
	v_pk_fma_f32 v[34:35], v[86:87], v[38:39], v[98:99]
	v_pk_fma_f32 v[34:35], v[30:31], v[90:91], v[34:35]
	v_pk_fma_f32 v[28:29], v[20:21], v[88:89], v[28:29]
	v_pk_fma_f32 v[34:35], v[22:23], v[94:95], v[34:35]
	v_pk_fma_f32 v[20:21], v[20:21], v[84:85], v[96:97]
	v_exp_f32_e32 v38, v34
	v_exp_f32_e32 v39, v35
	v_pk_fma_f32 v[28:29], v[12:13], v[92:93], v[28:29]
	v_pk_fma_f32 v[12:13], v[12:13], v[88:89], v[20:21]
	v_pk_fma_f32 v[36:37], v[64:65], v[48:49], v[80:81]
	v_add_f32_e32 v38, 1.0, v38
	v_add_f32_e32 v39, 1.0, v39
	v_pk_fma_f32 v[4:5], v[4:5], v[92:93], v[12:13]
	v_rcp_f32_e32 v38, v38
	v_rcp_f32_e32 v39, v39
	v_pk_fma_f32 v[36:37], v[24:25], v[68:69], v[36:37]
	v_pk_fma_f32 v[36:37], v[16:17], v[76:77], v[36:37]
	v_exp_f32_e32 v12, v4
	v_exp_f32_e32 v13, v5
	v_pk_mul_f32 v[32:33], v[36:37], v[32:33]
	v_pk_fma_f32 v[36:37], v[66:67], v[40:41], v[82:83]
	v_pk_fma_f32 v[36:37], v[26:27], v[70:71], v[36:37]
	v_pk_mul_f32 v[34:35], v[34:35], v[38:39]
	v_pk_fma_f32 v[36:37], v[18:19], v[78:79], v[36:37]
	v_add_f32_e32 v12, 1.0, v12
	v_pk_mul_f32 v[34:35], v[36:37], v[34:35]
	v_add_f32_e32 v13, 1.0, v13
	v_cvt_pk_bf16_f32 v32, v32, v33
	v_cvt_pk_bf16_f32 v33, v34, v35
	v_lshl_add_u64 v[34:35], v[124:125], 0, v[56:57]
	v_rcp_f32_e32 v12, v12
	v_rcp_f32_e32 v13, v13
	global_store_dwordx2 v[34:35], v[32:33], off
	v_exp_f32_e32 v34, v28
	v_mov_b32_e32 v32, v74
	v_exp_f32_e32 v35, v29
	v_mov_b32_e32 v33, v74
	v_mov_b32_e32 v74, v75
	v_pk_mul_f32 v[4:5], v[4:5], v[12:13]
	v_pk_fma_f32 v[12:13], v[22:23], v[86:87], v[98:99]
	v_pk_fma_f32 v[12:13], v[14:15], v[90:91], v[12:13]
	v_pk_fma_f32 v[30:31], v[30:31], v[86:87], v[98:99]
	v_pk_fma_f32 v[6:7], v[6:7], v[94:95], v[12:13]
	v_pk_fma_f32 v[30:31], v[22:23], v[90:91], v[30:31]
	v_pk_fma_f32 v[30:31], v[14:15], v[94:95], v[30:31]
	v_exp_f32_e32 v14, v6
	v_exp_f32_e32 v15, v7
	v_exp_f32_e32 v32, v30
	v_exp_f32_e32 v33, v31
	v_add_f32_e32 v14, 1.0, v14
	v_add_f32_e32 v15, 1.0, v15
	v_add_f32_e32 v34, 1.0, v34
	v_add_f32_e32 v35, 1.0, v35
	v_pk_fma_f32 v[24:25], v[24:25], v[64:65], v[80:81]
	v_rcp_f32_e32 v14, v14
	v_rcp_f32_e32 v15, v15
	v_rcp_f32_e32 v34, v34
	v_rcp_f32_e32 v35, v35
	v_add_f32_e32 v32, 1.0, v32
	v_add_f32_e32 v33, 1.0, v33
	v_pk_fma_f32 v[24:25], v[16:17], v[68:69], v[24:25]
	v_pk_fma_f32 v[12:13], v[16:17], v[64:65], v[80:81]
	v_rcp_f32_e32 v32, v32
	v_rcp_f32_e32 v33, v33
	v_pk_fma_f32 v[24:25], v[8:9], v[76:77], v[24:25]
	v_pk_fma_f32 v[8:9], v[8:9], v[68:69], v[12:13]
	v_pk_fma_f32 v[26:27], v[26:27], v[66:67], v[82:83]
	v_pk_fma_f32 v[0:1], v[0:1], v[76:77], v[8:9]
	v_pk_mul_f32 v[28:29], v[28:29], v[34:35]
	v_pk_mul_f32 v[0:1], v[0:1], v[4:5]
	v_pk_mul_f32 v[4:5], v[6:7], v[14:15]
	v_pk_fma_f32 v[6:7], v[18:19], v[66:67], v[82:83]
	v_pk_fma_f32 v[26:27], v[18:19], v[70:71], v[26:27]
	v_pk_fma_f32 v[6:7], v[10:11], v[70:71], v[6:7]
	v_pk_mul_f32 v[24:25], v[24:25], v[28:29]
	v_pk_mul_f32 v[28:29], v[30:31], v[32:33]
	v_pk_fma_f32 v[26:27], v[10:11], v[78:79], v[26:27]
	v_pk_fma_f32 v[2:3], v[2:3], v[78:79], v[6:7]
	v_pk_mul_f32 v[26:27], v[26:27], v[28:29]
	v_pk_mul_f32 v[2:3], v[2:3], v[4:5]
	v_cvt_pk_bf16_f32 v24, v24, v25
	v_cvt_pk_bf16_f32 v25, v26, v27
	v_lshl_add_u64 v[26:27], v[130:131], 0, v[56:57]
	v_cvt_pk_bf16_f32 v0, v0, v1
	v_cvt_pk_bf16_f32 v1, v2, v3
	v_lshl_add_u64 v[2:3], v[134:135], 0, v[56:57]
	global_store_dwordx2 v[26:27], v[24:25], off
	global_store_dwordx2 v[2:3], v[0:1], off
	s_and_b64 vcc, exec, s[6:7]
	s_mov_b64 s[0:1], -1
	s_cbranch_vccnz .LBB0_1543
	s_xor_b32 s4, s29, 0x400
	v_lshlrev_b32_e32 v0, 2, v226
	v_lshl_add_u32 v0, s4, 2, v0
	v_add_u32_e32 v0, 0x22040, v0
	v_cmp_gt_i32_e32 vcc, s33, v226
	s_waitcnt vmcnt(0)
	v_mul_f32_e32 v228, 0xbfb8aa3b, v228
	v_mul_f32_e32 v227, 0xbf317218, v227
	ds_write2st64_b32 v0, v228, v227 offset1:8
	s_and_saveexec_b64 s[0:1], vcc
	s_cbranch_execz .LBB0_1590
	v_rsq_f32_e32 v0, v229
	v_lshl_add_u32 v1, v226, 2, s4
	v_add_u32_e32 v1, 0x24040, v1
	ds_write_b32 v1, v0
